# v28 + GEMM MFMA clusters issued in snake order (consecutive MFMAs always share one operand fragment; same instructions, independent accumulators)
# speedup vs baseline: 1.0042x; 1.0042x over previous
.LBB0_104:
	s_add_u32 s10, s8, 0xfff00080
	s_addc_u32 s11, s9, -1
	s_add_i32 s34, 0, 0x10000
	s_cmp_eq_u32 s29, 60
	s_cselect_b32 s13, s7, s11
	s_cselect_b32 s12, s24, s10
	s_cselect_b32 s11, s25, s28
	s_cselect_b32 s10, s26, s27
	s_add_i32 s40, 0, 0x14000
	v_add_u32_e32 v158, s34, v162
	v_add_u32_e32 v172, s40, v162
	s_waitcnt lgkmcnt(0)
	ds_read_b128 v[132:135], v158
	ds_read_b128 v[136:139], v158 offset:1024
	ds_read_b128 v[154:157], v158 offset:2048
	ds_read_b128 v[158:161], v158 offset:3072
	ds_read_b128 v[184:187], v172
	ds_read_b128 v[188:191], v172 offset:1024
	ds_read_b128 v[192:195], v172 offset:2048
	ds_read_b128 v[196:199], v172 offset:3072
	v_lshl_add_u64 v[216:217], s[8:9], 0, v[150:151]
	s_add_i32 m0, s16, 0xc000
	ds_read_b128 v[200:203], v182
	ds_read_b128 v[204:207], v182 offset:1024
	ds_read_b128 v[208:211], v182 offset:2048
	ds_read_b128 v[212:215], v182 offset:3072
	ds_read_b128 v[232:235], v182 offset:4096
	ds_read_b128 v[236:239], v182 offset:5120
	ds_read_b128 v[240:243], v182 offset:6144
	ds_read_b128 v[244:247], v182 offset:7168
	global_load_lds_dwordx4 v[216:217], off
	v_lshl_add_u64 v[216:217], s[8:9], 0, v[152:153]
	s_add_i32 m0, s16, 0xe000
	s_nop 0
	global_load_lds_dwordx4 v[216:217], off
	s_waitcnt vmcnt(8)
	s_waitcnt lgkmcnt(0)
	s_barrier
	s_setprio 1
	s_waitcnt lgkmcnt(0)
	v_mfma_f32_16x16x32_bf16 v[128:131], v[132:135], v[200:203], v[128:131]
	v_mfma_f32_16x16x32_bf16 v[124:127], v[154:157], v[200:203], v[124:127]
	v_mfma_f32_16x16x32_bf16 v[108:111], v[154:157], v[208:211], v[108:111]
	v_mfma_f32_16x16x32_bf16 v[112:115], v[132:135], v[208:211], v[112:115]
	v_mfma_f32_16x16x32_bf16 v[96:99], v[132:135], v[232:235], v[96:99]
	v_mfma_f32_16x16x32_bf16 v[92:95], v[154:157], v[232:235], v[92:95]
	v_mfma_f32_16x16x32_bf16 v[76:79], v[154:157], v[240:243], v[76:79]
	v_mfma_f32_16x16x32_bf16 v[80:83], v[132:135], v[240:243], v[80:83]
	v_mfma_f32_16x16x32_bf16 v[128:131], v[136:139], v[204:207], v[128:131]
	v_mfma_f32_16x16x32_bf16 v[124:127], v[158:161], v[204:207], v[124:127]
	v_mfma_f32_16x16x32_bf16 v[108:111], v[158:161], v[212:215], v[108:111]
	v_mfma_f32_16x16x32_bf16 v[112:115], v[136:139], v[212:215], v[112:115]
	v_mfma_f32_16x16x32_bf16 v[96:99], v[136:139], v[236:239], v[96:99]
	v_mfma_f32_16x16x32_bf16 v[92:95], v[158:161], v[236:239], v[92:95]
	v_mfma_f32_16x16x32_bf16 v[76:79], v[158:161], v[244:247], v[76:79]
	v_mfma_f32_16x16x32_bf16 v[80:83], v[136:139], v[244:247], v[80:83]
	s_setprio 0
	s_setprio 1
	v_mfma_f32_16x16x32_bf16 v[120:123], v[184:187], v[200:203], v[120:123]
	v_mfma_f32_16x16x32_bf16 v[116:119], v[192:195], v[200:203], v[116:119]
	v_mfma_f32_16x16x32_bf16 v[100:103], v[192:195], v[208:211], v[100:103]
	v_mfma_f32_16x16x32_bf16 v[104:107], v[184:187], v[208:211], v[104:107]
	v_mfma_f32_16x16x32_bf16 v[88:91], v[184:187], v[232:235], v[88:91]
	v_mfma_f32_16x16x32_bf16 v[84:87], v[192:195], v[232:235], v[84:87]
	v_mfma_f32_16x16x32_bf16 v[68:71], v[192:195], v[240:243], v[68:71]
	v_mfma_f32_16x16x32_bf16 v[72:75], v[184:187], v[240:243], v[72:75]
	v_mfma_f32_16x16x32_bf16 v[120:123], v[188:191], v[204:207], v[120:123]
	v_mfma_f32_16x16x32_bf16 v[116:119], v[196:199], v[204:207], v[116:119]
	v_mfma_f32_16x16x32_bf16 v[100:103], v[196:199], v[212:215], v[100:103]
	v_mfma_f32_16x16x32_bf16 v[104:107], v[188:191], v[212:215], v[104:107]
	v_mfma_f32_16x16x32_bf16 v[88:91], v[188:191], v[236:239], v[88:91]
	v_mfma_f32_16x16x32_bf16 v[84:87], v[196:199], v[236:239], v[84:87]
	v_mfma_f32_16x16x32_bf16 v[68:71], v[196:199], v[244:247], v[68:71]
	v_mfma_f32_16x16x32_bf16 v[72:75], v[188:191], v[244:247], v[72:75]
	s_setprio 0
	s_barrier
	s_add_i32 s34, s34, s15
	v_lshl_add_u64 v[216:217], s[10:11], 0, v[142:143]
	s_mov_b32 m0, s34
	ds_read_b128 v[200:203], v182 offset:16384
	ds_read_b128 v[204:207], v182 offset:17408
	ds_read_b128 v[208:211], v182 offset:18432
	ds_read_b128 v[212:215], v182 offset:19456
	ds_read_b128 v[232:235], v182 offset:20480
	ds_read_b128 v[236:239], v182 offset:21504
	ds_read_b128 v[240:243], v182 offset:22528
	ds_read_b128 v[244:247], v182 offset:23552
	global_load_lds_dwordx4 v[216:217], off
	s_add_i32 m0, s34, 0x2000
	s_add_u32 s34, s10, 0x100000
	v_lshl_add_u64 v[220:221], s[10:11], 0, v[146:147]
	s_addc_u32 s35, s11, 0
	s_add_i32 s40, s40, s15
	global_load_lds_dwordx4 v[220:221], off
	v_lshl_add_u64 v[172:173], s[34:35], 0, v[142:143]
	s_mov_b32 m0, s40
	v_lshl_add_u64 v[174:175], s[12:13], 0, v[144:145]
	global_load_lds_dwordx4 v[172:173], off
	v_lshl_add_u64 v[172:173], s[34:35], 0, v[146:147]
	s_add_i32 m0, s40, 0x2000
	s_nop 0
	global_load_lds_dwordx4 v[172:173], off
	v_lshl_add_u64 v[172:173], s[12:13], 0, v[140:141]
	s_mov_b32 m0, s16
	s_nop 0
	global_load_lds_dwordx4 v[172:173], off
	s_mov_b32 m0, s17
	s_nop 0
	global_load_lds_dwordx4 v[174:175], off
	s_waitcnt vmcnt(8)
	s_waitcnt lgkmcnt(0)
	s_barrier
	s_setprio 1
	s_waitcnt lgkmcnt(0)
	v_mfma_f32_16x16x32_bf16 v[64:67], v[132:135], v[200:203], v[64:67]
	v_mfma_f32_16x16x32_bf16 v[60:63], v[154:157], v[200:203], v[60:63]
	v_mfma_f32_16x16x32_bf16 v[44:47], v[154:157], v[208:211], v[44:47]
	v_mfma_f32_16x16x32_bf16 v[48:51], v[132:135], v[208:211], v[48:51]
	v_mfma_f32_16x16x32_bf16 v[30:33], v[132:135], v[232:235], v[30:33]
	v_mfma_f32_16x16x32_bf16 v[26:29], v[154:157], v[232:235], v[26:29]
	v_mfma_f32_16x16x32_bf16 v[10:13], v[154:157], v[240:243], v[10:13]
	v_mfma_f32_16x16x32_bf16 v[14:17], v[132:135], v[240:243], v[14:17]
	v_mfma_f32_16x16x32_bf16 v[64:67], v[136:139], v[204:207], v[64:67]
	v_mfma_f32_16x16x32_bf16 v[60:63], v[158:161], v[204:207], v[60:63]
	v_mfma_f32_16x16x32_bf16 v[44:47], v[158:161], v[212:215], v[44:47]
	v_mfma_f32_16x16x32_bf16 v[48:51], v[136:139], v[212:215], v[48:51]
	v_mfma_f32_16x16x32_bf16 v[30:33], v[136:139], v[236:239], v[30:33]
	v_mfma_f32_16x16x32_bf16 v[26:29], v[158:161], v[236:239], v[26:29]
	v_mfma_f32_16x16x32_bf16 v[10:13], v[158:161], v[244:247], v[10:13]
	v_mfma_f32_16x16x32_bf16 v[14:17], v[136:139], v[244:247], v[14:17]
	s_setprio 0
	s_setprio 1
	v_mfma_f32_16x16x32_bf16 v[56:59], v[184:187], v[200:203], v[56:59]
	v_mfma_f32_16x16x32_bf16 v[52:55], v[192:195], v[200:203], v[52:55]
	v_mfma_f32_16x16x32_bf16 v[36:39], v[192:195], v[208:211], v[36:39]
	v_mfma_f32_16x16x32_bf16 v[40:43], v[184:187], v[208:211], v[40:43]
	v_mfma_f32_16x16x32_bf16 v[22:25], v[184:187], v[232:235], v[22:25]
	v_mfma_f32_16x16x32_bf16 v[18:21], v[192:195], v[232:235], v[18:21]
	v_mfma_f32_16x16x32_bf16 v[2:5], v[192:195], v[240:243], v[2:5]
	v_mfma_f32_16x16x32_bf16 v[6:9], v[184:187], v[240:243], v[6:9]
	v_mfma_f32_16x16x32_bf16 v[56:59], v[188:191], v[204:207], v[56:59]
	v_mfma_f32_16x16x32_bf16 v[52:55], v[196:199], v[204:207], v[52:55]
	v_mfma_f32_16x16x32_bf16 v[36:39], v[196:199], v[212:215], v[36:39]
	v_mfma_f32_16x16x32_bf16 v[40:43], v[188:191], v[212:215], v[40:43]
	v_mfma_f32_16x16x32_bf16 v[22:25], v[188:191], v[236:239], v[22:25]
	v_mfma_f32_16x16x32_bf16 v[18:21], v[196:199], v[236:239], v[18:21]
	v_mfma_f32_16x16x32_bf16 v[2:5], v[196:199], v[244:247], v[2:5]
	v_mfma_f32_16x16x32_bf16 v[6:9], v[188:191], v[244:247], v[6:9]
	s_setprio 0
	s_barrier
	s_add_i32 s34, 0, 0x18000
	s_add_i32 s35, 0, 0x1c000
	v_add_u32_e32 v158, s34, v162
	v_add_u32_e32 v176, s35, v162
	ds_read_b128 v[132:135], v158
	ds_read_b128 v[136:139], v158 offset:1024
	ds_read_b128 v[154:157], v158 offset:2048
	ds_read_b128 v[158:161], v158 offset:3072
	ds_read_b128 v[184:187], v176
	ds_read_b128 v[188:191], v176 offset:1024
	ds_read_b128 v[192:195], v176 offset:2048
	ds_read_b128 v[196:199], v176 offset:3072
	s_add_u32 s12, s12, 0x100000
	s_addc_u32 s13, s13, 0
	s_mov_b32 m0, s18
	v_lshl_add_u64 v[176:177], s[12:13], 0, v[140:141]
	ds_read_b128 v[200:203], v182 offset:32768
	ds_read_b128 v[204:207], v182 offset:33792
	ds_read_b128 v[208:211], v182 offset:34816
	ds_read_b128 v[212:215], v182 offset:35840
	ds_read_b128 v[232:235], v182 offset:36864
	ds_read_b128 v[236:239], v182 offset:37888
	ds_read_b128 v[240:243], v182 offset:38912
	ds_read_b128 v[244:247], v182 offset:39936
	global_load_lds_dwordx4 v[176:177], off
	v_lshl_add_u64 v[176:177], s[12:13], 0, v[144:145]
	s_mov_b32 m0, s19
	s_nop 0
	global_load_lds_dwordx4 v[176:177], off
	s_waitcnt vmcnt(8)
	s_waitcnt lgkmcnt(0)
	s_barrier
	s_setprio 1
	s_waitcnt lgkmcnt(0)
	v_mfma_f32_16x16x32_bf16 v[128:131], v[132:135], v[200:203], v[128:131]
	v_mfma_f32_16x16x32_bf16 v[124:127], v[154:157], v[200:203], v[124:127]
	v_mfma_f32_16x16x32_bf16 v[108:111], v[154:157], v[208:211], v[108:111]
	v_mfma_f32_16x16x32_bf16 v[112:115], v[132:135], v[208:211], v[112:115]
	v_mfma_f32_16x16x32_bf16 v[96:99], v[132:135], v[232:235], v[96:99]
	v_mfma_f32_16x16x32_bf16 v[92:95], v[154:157], v[232:235], v[92:95]
	v_mfma_f32_16x16x32_bf16 v[76:79], v[154:157], v[240:243], v[76:79]
	v_mfma_f32_16x16x32_bf16 v[80:83], v[132:135], v[240:243], v[80:83]
	v_mfma_f32_16x16x32_bf16 v[128:131], v[136:139], v[204:207], v[128:131]
	v_mfma_f32_16x16x32_bf16 v[124:127], v[158:161], v[204:207], v[124:127]
	v_mfma_f32_16x16x32_bf16 v[108:111], v[158:161], v[212:215], v[108:111]
	v_mfma_f32_16x16x32_bf16 v[112:115], v[136:139], v[212:215], v[112:115]
	v_mfma_f32_16x16x32_bf16 v[96:99], v[136:139], v[236:239], v[96:99]
	v_mfma_f32_16x16x32_bf16 v[92:95], v[158:161], v[236:239], v[92:95]
	v_mfma_f32_16x16x32_bf16 v[76:79], v[158:161], v[244:247], v[76:79]
	v_mfma_f32_16x16x32_bf16 v[80:83], v[136:139], v[244:247], v[80:83]
	s_setprio 0
	s_setprio 1
	v_mfma_f32_16x16x32_bf16 v[120:123], v[184:187], v[200:203], v[120:123]
	v_mfma_f32_16x16x32_bf16 v[116:119], v[192:195], v[200:203], v[116:119]
	v_mfma_f32_16x16x32_bf16 v[100:103], v[192:195], v[208:211], v[100:103]
	v_mfma_f32_16x16x32_bf16 v[104:107], v[184:187], v[208:211], v[104:107]
	v_mfma_f32_16x16x32_bf16 v[88:91], v[184:187], v[232:235], v[88:91]
	v_mfma_f32_16x16x32_bf16 v[84:87], v[192:195], v[232:235], v[84:87]
	v_mfma_f32_16x16x32_bf16 v[68:71], v[192:195], v[240:243], v[68:71]
	v_mfma_f32_16x16x32_bf16 v[72:75], v[184:187], v[240:243], v[72:75]
	v_mfma_f32_16x16x32_bf16 v[120:123], v[188:191], v[204:207], v[120:123]
	v_mfma_f32_16x16x32_bf16 v[116:119], v[196:199], v[204:207], v[116:119]
	v_mfma_f32_16x16x32_bf16 v[100:103], v[196:199], v[212:215], v[100:103]
	v_mfma_f32_16x16x32_bf16 v[104:107], v[188:191], v[212:215], v[104:107]
	v_mfma_f32_16x16x32_bf16 v[88:91], v[188:191], v[236:239], v[88:91]
	v_mfma_f32_16x16x32_bf16 v[84:87], v[196:199], v[236:239], v[84:87]
	v_mfma_f32_16x16x32_bf16 v[68:71], v[196:199], v[244:247], v[68:71]
	v_mfma_f32_16x16x32_bf16 v[72:75], v[188:191], v[244:247], v[72:75]
	s_setprio 0
	s_barrier
	s_add_i32 s12, s34, s15
	v_lshl_add_u64 v[176:177], v[216:217], 0, s[2:3]
	s_mov_b32 m0, s12
	ds_read_b128 v[200:203], v182 offset:49152
	ds_read_b128 v[204:207], v182 offset:50176
	ds_read_b128 v[208:211], v182 offset:51200
	ds_read_b128 v[212:215], v182 offset:52224
	ds_read_b128 v[232:235], v182 offset:53248
	ds_read_b128 v[236:239], v182 offset:54272
	ds_read_b128 v[240:243], v182 offset:55296
	ds_read_b128 v[244:247], v182 offset:56320
	global_load_lds_dwordx4 v[176:177], off
	s_add_i32 m0, s12, 0x2000
	s_add_u32 s10, s10, 0x100080
	v_lshl_add_u64 v[176:177], v[220:221], 0, s[2:3]
	s_addc_u32 s11, s11, 0
	s_add_i32 s12, s35, s15
	global_load_lds_dwordx4 v[176:177], off
	v_lshl_add_u64 v[176:177], s[10:11], 0, v[142:143]
	s_mov_b32 m0, s12
	v_lshl_add_u64 v[172:173], v[172:173], 0, s[2:3]
	global_load_lds_dwordx4 v[176:177], off
	v_lshl_add_u64 v[176:177], s[10:11], 0, v[146:147]
	s_add_i32 m0, s12, 0x2000
	s_nop 0
	global_load_lds_dwordx4 v[176:177], off
	s_mov_b32 m0, s20
	s_nop 0
	global_load_lds_dwordx4 v[172:173], off
	v_lshl_add_u64 v[172:173], v[174:175], 0, s[2:3]
	s_mov_b32 m0, s21
	s_nop 0
	global_load_lds_dwordx4 v[172:173], off
	s_waitcnt vmcnt(8)
	s_waitcnt lgkmcnt(0)
	s_barrier
	s_setprio 1
	s_waitcnt lgkmcnt(0)
	v_mfma_f32_16x16x32_bf16 v[64:67], v[132:135], v[200:203], v[64:67]
	v_mfma_f32_16x16x32_bf16 v[60:63], v[154:157], v[200:203], v[60:63]
	v_mfma_f32_16x16x32_bf16 v[44:47], v[154:157], v[208:211], v[44:47]
	v_mfma_f32_16x16x32_bf16 v[48:51], v[132:135], v[208:211], v[48:51]
	v_mfma_f32_16x16x32_bf16 v[30:33], v[132:135], v[232:235], v[30:33]
	v_mfma_f32_16x16x32_bf16 v[26:29], v[154:157], v[232:235], v[26:29]
	v_mfma_f32_16x16x32_bf16 v[10:13], v[154:157], v[240:243], v[10:13]
	v_mfma_f32_16x16x32_bf16 v[14:17], v[132:135], v[240:243], v[14:17]
	v_mfma_f32_16x16x32_bf16 v[64:67], v[136:139], v[204:207], v[64:67]
	v_mfma_f32_16x16x32_bf16 v[60:63], v[158:161], v[204:207], v[60:63]
	v_mfma_f32_16x16x32_bf16 v[44:47], v[158:161], v[212:215], v[44:47]
	v_mfma_f32_16x16x32_bf16 v[48:51], v[136:139], v[212:215], v[48:51]
	v_mfma_f32_16x16x32_bf16 v[30:33], v[136:139], v[236:239], v[30:33]
	v_mfma_f32_16x16x32_bf16 v[26:29], v[158:161], v[236:239], v[26:29]
	v_mfma_f32_16x16x32_bf16 v[10:13], v[158:161], v[244:247], v[10:13]
	v_mfma_f32_16x16x32_bf16 v[14:17], v[136:139], v[244:247], v[14:17]
	s_setprio 0
	s_setprio 1
	v_mfma_f32_16x16x32_bf16 v[56:59], v[184:187], v[200:203], v[56:59]
	v_mfma_f32_16x16x32_bf16 v[52:55], v[192:195], v[200:203], v[52:55]
	v_mfma_f32_16x16x32_bf16 v[36:39], v[192:195], v[208:211], v[36:39]
	v_mfma_f32_16x16x32_bf16 v[40:43], v[184:187], v[208:211], v[40:43]
	v_mfma_f32_16x16x32_bf16 v[22:25], v[184:187], v[232:235], v[22:25]
	v_mfma_f32_16x16x32_bf16 v[18:21], v[192:195], v[232:235], v[18:21]
	v_mfma_f32_16x16x32_bf16 v[2:5], v[192:195], v[240:243], v[2:5]
	v_mfma_f32_16x16x32_bf16 v[6:9], v[184:187], v[240:243], v[6:9]
	v_mfma_f32_16x16x32_bf16 v[56:59], v[188:191], v[204:207], v[56:59]
	v_mfma_f32_16x16x32_bf16 v[52:55], v[196:199], v[204:207], v[52:55]
	v_mfma_f32_16x16x32_bf16 v[36:39], v[196:199], v[212:215], v[36:39]
	v_mfma_f32_16x16x32_bf16 v[40:43], v[188:191], v[212:215], v[40:43]
	v_mfma_f32_16x16x32_bf16 v[22:25], v[188:191], v[236:239], v[22:25]
	v_mfma_f32_16x16x32_bf16 v[18:21], v[196:199], v[236:239], v[18:21]
	v_mfma_f32_16x16x32_bf16 v[2:5], v[196:199], v[244:247], v[2:5]
	v_mfma_f32_16x16x32_bf16 v[6:9], v[188:191], v[244:247], v[6:9]
	s_setprio 0
	s_barrier
	s_add_i32 s29, s29, 2
	s_add_u32 s8, s8, 0x100
	s_addc_u32 s9, s9, 0
	s_add_u32 s27, s27, 0x100
	s_addc_u32 s28, s28, 0
	s_cmp_gt_u32 s29, 61
	s_cbranch_scc0 .LBB0_104
	s_and_b64 vcc, exec, s[66:67]
	s_cbranch_vccnz .LBB0_109
	v_lshl_add_u32 v154, s6, 8, v35
	s_cmp_gt_i32 s76, 7
	s_mov_b64 s[6:7], -1
	s_cbranch_scc1 .LBB0_110

.LBB0_1446:
	s_add_u32 s10, s26, s8
	s_addc_u32 s11, s27, s9
	s_add_u32 s10, s10, 0x55a00100
	s_addc_u32 s11, s11, 0
	s_add_u32 s29, s24, s8
	s_addc_u32 s30, s25, s9
	s_add_i32 s31, 0, 0x10000
	s_cmpk_eq_i32 s8, 0xf00
	s_cselect_b32 s13, s7, s11
	s_cselect_b32 s12, s6, s10
	v_add_u32_e32 v1, s31, v146
	s_cselect_b32 s11, s1, s30
	s_cselect_b32 s10, s0, s29
	s_add_i32 s29, 0, 0x14000
	ds_read_b128 v[148:151], v1
	ds_read_b128 v[152:155], v1 offset:1024
	ds_read_b128 v[156:159], v1 offset:2048
	ds_read_b128 v[160:163], v1 offset:3072
	v_add_u32_e32 v1, s29, v146
	ds_read_b128 v[172:175], v1
	ds_read_b128 v[176:179], v1 offset:1024
	ds_read_b128 v[180:183], v1 offset:2048
	ds_read_b128 v[184:187], v1 offset:3072
	v_lshl_add_u64 v[216:217], v[144:145], 0, s[8:9]
	s_add_i32 m0, s16, 0xc000
	ds_read_b128 v[188:191], v147
	ds_read_b128 v[192:195], v147 offset:1024
	ds_read_b128 v[196:199], v147 offset:2048
	ds_read_b128 v[200:203], v147 offset:3072
	ds_read_b128 v[204:207], v147 offset:4096
	ds_read_b128 v[208:211], v147 offset:5120
	ds_read_b128 v[212:215], v147 offset:6144
	ds_read_b128 v[232:235], v147 offset:7168
	global_load_lds_dwordx4 v[216:217], off
	v_lshl_add_u64 v[216:217], v[142:143], 0, s[8:9]
	s_add_i32 m0, s16, 0xe000
	s_nop 0
	global_load_lds_dwordx4 v[216:217], off
	s_waitcnt vmcnt(8)
	s_waitcnt lgkmcnt(0)
	s_barrier
	s_setprio 1
	s_waitcnt lgkmcnt(0)
	v_mfma_f32_16x16x32_bf16 v[128:131], v[148:151], v[188:191], v[128:131]
	v_mfma_f32_16x16x32_bf16 v[124:127], v[156:159], v[188:191], v[124:127]
	v_mfma_f32_16x16x32_bf16 v[108:111], v[156:159], v[196:199], v[108:111]
	v_mfma_f32_16x16x32_bf16 v[116:119], v[148:151], v[196:199], v[116:119]
	v_mfma_f32_16x16x32_bf16 v[100:103], v[148:151], v[204:207], v[100:103]
	v_mfma_f32_16x16x32_bf16 v[92:95], v[156:159], v[204:207], v[92:95]
	v_mfma_f32_16x16x32_bf16 v[76:79], v[156:159], v[212:215], v[76:79]
	v_mfma_f32_16x16x32_bf16 v[84:87], v[148:151], v[212:215], v[84:87]
	v_mfma_f32_16x16x32_bf16 v[128:131], v[152:155], v[192:195], v[128:131]
	v_mfma_f32_16x16x32_bf16 v[124:127], v[160:163], v[192:195], v[124:127]
	v_mfma_f32_16x16x32_bf16 v[108:111], v[160:163], v[200:203], v[108:111]
	v_mfma_f32_16x16x32_bf16 v[116:119], v[152:155], v[200:203], v[116:119]
	v_mfma_f32_16x16x32_bf16 v[100:103], v[152:155], v[208:211], v[100:103]
	v_mfma_f32_16x16x32_bf16 v[92:95], v[160:163], v[208:211], v[92:95]
	v_mfma_f32_16x16x32_bf16 v[76:79], v[160:163], v[232:235], v[76:79]
	v_mfma_f32_16x16x32_bf16 v[84:87], v[152:155], v[232:235], v[84:87]
	s_setprio 0
	s_setprio 1
	v_mfma_f32_16x16x32_bf16 v[120:123], v[172:175], v[188:191], v[120:123]
	v_mfma_f32_16x16x32_bf16 v[112:115], v[180:183], v[188:191], v[112:115]
	v_mfma_f32_16x16x32_bf16 v[96:99], v[180:183], v[196:199], v[96:99]
	v_mfma_f32_16x16x32_bf16 v[104:107], v[172:175], v[196:199], v[104:107]
	v_mfma_f32_16x16x32_bf16 v[88:91], v[172:175], v[204:207], v[88:91]
	v_mfma_f32_16x16x32_bf16 v[80:83], v[180:183], v[204:207], v[80:83]
	v_mfma_f32_16x16x32_bf16 v[68:71], v[180:183], v[212:215], v[68:71]
	v_mfma_f32_16x16x32_bf16 v[72:75], v[172:175], v[212:215], v[72:75]
	v_mfma_f32_16x16x32_bf16 v[120:123], v[176:179], v[192:195], v[120:123]
	v_mfma_f32_16x16x32_bf16 v[112:115], v[184:187], v[192:195], v[112:115]
	v_mfma_f32_16x16x32_bf16 v[96:99], v[184:187], v[200:203], v[96:99]
	v_mfma_f32_16x16x32_bf16 v[104:107], v[176:179], v[200:203], v[104:107]
	v_mfma_f32_16x16x32_bf16 v[88:91], v[176:179], v[208:211], v[88:91]
	v_mfma_f32_16x16x32_bf16 v[80:83], v[184:187], v[208:211], v[80:83]
	v_mfma_f32_16x16x32_bf16 v[68:71], v[184:187], v[232:235], v[68:71]
	v_mfma_f32_16x16x32_bf16 v[72:75], v[176:179], v[232:235], v[72:75]
	s_setprio 0
	s_barrier
	s_add_i32 s30, s31, s15
	v_lshl_add_u64 v[216:217], s[10:11], 0, v[134:135]
	s_mov_b32 m0, s30
	ds_read_b128 v[188:191], v147 offset:16384
	ds_read_b128 v[192:195], v147 offset:17408
	ds_read_b128 v[196:199], v147 offset:18432
	ds_read_b128 v[200:203], v147 offset:19456
	ds_read_b128 v[204:207], v147 offset:20480
	ds_read_b128 v[208:211], v147 offset:21504
	ds_read_b128 v[212:215], v147 offset:22528
	ds_read_b128 v[232:235], v147 offset:23552
	global_load_lds_dwordx4 v[216:217], off
	s_add_i32 m0, s30, 0x2000
	s_add_u32 s30, s10, 0x180000
	v_lshl_add_u64 v[220:221], s[10:11], 0, v[138:139]
	s_addc_u32 s31, s11, 0
	s_add_i32 s29, s29, s15
	global_load_lds_dwordx4 v[220:221], off
	v_lshl_add_u64 v[236:237], s[30:31], 0, v[134:135]
	s_mov_b32 m0, s29
	v_lshl_add_u64 v[238:239], s[12:13], 0, v[136:137]
	global_load_lds_dwordx4 v[236:237], off
	v_lshl_add_u64 v[236:237], s[30:31], 0, v[138:139]
	s_add_i32 m0, s29, 0x2000
	s_nop 0
	global_load_lds_dwordx4 v[236:237], off
	v_lshl_add_u64 v[236:237], s[12:13], 0, v[132:133]
	s_mov_b32 m0, s16
	s_nop 0
	global_load_lds_dwordx4 v[236:237], off
	s_mov_b32 m0, s17
	s_nop 0
	global_load_lds_dwordx4 v[238:239], off
	s_waitcnt vmcnt(8)
	s_waitcnt lgkmcnt(0)
	s_barrier
	s_setprio 1
	s_waitcnt lgkmcnt(0)
	v_mfma_f32_16x16x32_bf16 v[64:67], v[148:151], v[188:191], v[64:67]
	v_mfma_f32_16x16x32_bf16 v[60:63], v[156:159], v[188:191], v[60:63]
	v_mfma_f32_16x16x32_bf16 v[44:47], v[156:159], v[196:199], v[44:47]
	v_mfma_f32_16x16x32_bf16 v[52:55], v[148:151], v[196:199], v[52:55]
	v_mfma_f32_16x16x32_bf16 v[36:39], v[148:151], v[204:207], v[36:39]
	v_mfma_f32_16x16x32_bf16 v[26:29], v[156:159], v[204:207], v[26:29]
	v_mfma_f32_16x16x32_bf16 v[10:13], v[156:159], v[212:215], v[10:13]
	v_mfma_f32_16x16x32_bf16 v[18:21], v[148:151], v[212:215], v[18:21]
	v_mfma_f32_16x16x32_bf16 v[64:67], v[152:155], v[192:195], v[64:67]
	v_mfma_f32_16x16x32_bf16 v[60:63], v[160:163], v[192:195], v[60:63]
	v_mfma_f32_16x16x32_bf16 v[44:47], v[160:163], v[200:203], v[44:47]
	v_mfma_f32_16x16x32_bf16 v[52:55], v[152:155], v[200:203], v[52:55]
	v_mfma_f32_16x16x32_bf16 v[36:39], v[152:155], v[208:211], v[36:39]
	v_mfma_f32_16x16x32_bf16 v[26:29], v[160:163], v[208:211], v[26:29]
	v_mfma_f32_16x16x32_bf16 v[10:13], v[160:163], v[232:235], v[10:13]
	v_mfma_f32_16x16x32_bf16 v[18:21], v[152:155], v[232:235], v[18:21]
	s_setprio 0
	s_setprio 1
	v_mfma_f32_16x16x32_bf16 v[56:59], v[172:175], v[188:191], v[56:59]
	v_mfma_f32_16x16x32_bf16 v[48:51], v[180:183], v[188:191], v[48:51]
	v_mfma_f32_16x16x32_bf16 v[30:33], v[180:183], v[196:199], v[30:33]
	v_mfma_f32_16x16x32_bf16 v[40:43], v[172:175], v[196:199], v[40:43]
	v_mfma_f32_16x16x32_bf16 v[22:25], v[172:175], v[204:207], v[22:25]
	v_mfma_f32_16x16x32_bf16 v[14:17], v[180:183], v[204:207], v[14:17]
	v_mfma_f32_16x16x32_bf16 v[2:5], v[180:183], v[212:215], v[2:5]
	v_mfma_f32_16x16x32_bf16 v[6:9], v[172:175], v[212:215], v[6:9]
	v_mfma_f32_16x16x32_bf16 v[56:59], v[176:179], v[192:195], v[56:59]
	v_mfma_f32_16x16x32_bf16 v[48:51], v[184:187], v[192:195], v[48:51]
	v_mfma_f32_16x16x32_bf16 v[30:33], v[184:187], v[200:203], v[30:33]
	v_mfma_f32_16x16x32_bf16 v[40:43], v[176:179], v[200:203], v[40:43]
	v_mfma_f32_16x16x32_bf16 v[22:25], v[176:179], v[208:211], v[22:25]
	v_mfma_f32_16x16x32_bf16 v[14:17], v[184:187], v[208:211], v[14:17]
	v_mfma_f32_16x16x32_bf16 v[2:5], v[184:187], v[232:235], v[2:5]
	v_mfma_f32_16x16x32_bf16 v[6:9], v[176:179], v[232:235], v[6:9]
	s_setprio 0
	s_barrier
	s_add_i32 s29, 0, 0x18000
	v_add_u32_e32 v1, s29, v146
	s_add_i32 s30, 0, 0x1c000
	ds_read_b128 v[148:151], v1
	ds_read_b128 v[152:155], v1 offset:1024
	ds_read_b128 v[156:159], v1 offset:2048
	ds_read_b128 v[160:163], v1 offset:3072
	v_add_u32_e32 v1, s30, v146
	ds_read_b128 v[172:175], v1
	ds_read_b128 v[176:179], v1 offset:1024
	ds_read_b128 v[180:183], v1 offset:2048
	ds_read_b128 v[184:187], v1 offset:3072
	s_add_u32 s12, s12, 0x180000
	s_addc_u32 s13, s13, 0
	s_mov_b32 m0, s18
	v_lshl_add_u64 v[240:241], s[12:13], 0, v[132:133]
	ds_read_b128 v[188:191], v147 offset:32768
	ds_read_b128 v[192:195], v147 offset:33792
	ds_read_b128 v[196:199], v147 offset:34816
	ds_read_b128 v[200:203], v147 offset:35840
	ds_read_b128 v[204:207], v147 offset:36864
	ds_read_b128 v[208:211], v147 offset:37888
	ds_read_b128 v[212:215], v147 offset:38912
	ds_read_b128 v[232:235], v147 offset:39936
	global_load_lds_dwordx4 v[240:241], off
	v_lshl_add_u64 v[240:241], s[12:13], 0, v[136:137]
	s_mov_b32 m0, s19
	s_nop 0
	global_load_lds_dwordx4 v[240:241], off
	s_waitcnt vmcnt(8)
	s_waitcnt lgkmcnt(0)
	s_barrier
	s_setprio 1
	s_waitcnt lgkmcnt(0)
	v_mfma_f32_16x16x32_bf16 v[128:131], v[148:151], v[188:191], v[128:131]
	v_mfma_f32_16x16x32_bf16 v[124:127], v[156:159], v[188:191], v[124:127]
	v_mfma_f32_16x16x32_bf16 v[108:111], v[156:159], v[196:199], v[108:111]
	v_mfma_f32_16x16x32_bf16 v[116:119], v[148:151], v[196:199], v[116:119]
	v_mfma_f32_16x16x32_bf16 v[100:103], v[148:151], v[204:207], v[100:103]
	v_mfma_f32_16x16x32_bf16 v[92:95], v[156:159], v[204:207], v[92:95]
	v_mfma_f32_16x16x32_bf16 v[76:79], v[156:159], v[212:215], v[76:79]
	v_mfma_f32_16x16x32_bf16 v[84:87], v[148:151], v[212:215], v[84:87]
	v_mfma_f32_16x16x32_bf16 v[128:131], v[152:155], v[192:195], v[128:131]
	v_mfma_f32_16x16x32_bf16 v[124:127], v[160:163], v[192:195], v[124:127]
	v_mfma_f32_16x16x32_bf16 v[108:111], v[160:163], v[200:203], v[108:111]
	v_mfma_f32_16x16x32_bf16 v[116:119], v[152:155], v[200:203], v[116:119]
	v_mfma_f32_16x16x32_bf16 v[100:103], v[152:155], v[208:211], v[100:103]
	v_mfma_f32_16x16x32_bf16 v[92:95], v[160:163], v[208:211], v[92:95]
	v_mfma_f32_16x16x32_bf16 v[76:79], v[160:163], v[232:235], v[76:79]
	v_mfma_f32_16x16x32_bf16 v[84:87], v[152:155], v[232:235], v[84:87]
	s_setprio 0
	s_setprio 1
	v_mfma_f32_16x16x32_bf16 v[120:123], v[172:175], v[188:191], v[120:123]
	v_mfma_f32_16x16x32_bf16 v[112:115], v[180:183], v[188:191], v[112:115]
	v_mfma_f32_16x16x32_bf16 v[96:99], v[180:183], v[196:199], v[96:99]
	v_mfma_f32_16x16x32_bf16 v[104:107], v[172:175], v[196:199], v[104:107]
	v_mfma_f32_16x16x32_bf16 v[88:91], v[172:175], v[204:207], v[88:91]
	v_mfma_f32_16x16x32_bf16 v[80:83], v[180:183], v[204:207], v[80:83]
	v_mfma_f32_16x16x32_bf16 v[68:71], v[180:183], v[212:215], v[68:71]
	v_mfma_f32_16x16x32_bf16 v[72:75], v[172:175], v[212:215], v[72:75]
	v_mfma_f32_16x16x32_bf16 v[120:123], v[176:179], v[192:195], v[120:123]
	v_mfma_f32_16x16x32_bf16 v[112:115], v[184:187], v[192:195], v[112:115]
	v_mfma_f32_16x16x32_bf16 v[96:99], v[184:187], v[200:203], v[96:99]
	v_mfma_f32_16x16x32_bf16 v[104:107], v[176:179], v[200:203], v[104:107]
	v_mfma_f32_16x16x32_bf16 v[88:91], v[176:179], v[208:211], v[88:91]
	v_mfma_f32_16x16x32_bf16 v[80:83], v[184:187], v[208:211], v[80:83]
	v_mfma_f32_16x16x32_bf16 v[68:71], v[184:187], v[232:235], v[68:71]
	v_mfma_f32_16x16x32_bf16 v[72:75], v[176:179], v[232:235], v[72:75]
	s_setprio 0
	s_barrier
	s_add_i32 s12, s29, s15
	v_lshl_add_u64 v[216:217], v[216:217], 0, s[2:3]
	s_mov_b32 m0, s12
	ds_read_b128 v[188:191], v147 offset:49152
	ds_read_b128 v[192:195], v147 offset:50176
	ds_read_b128 v[196:199], v147 offset:51200
	ds_read_b128 v[200:203], v147 offset:52224
	ds_read_b128 v[204:207], v147 offset:53248
	ds_read_b128 v[208:211], v147 offset:54272
	ds_read_b128 v[212:215], v147 offset:55296
	ds_read_b128 v[232:235], v147 offset:56320
	global_load_lds_dwordx4 v[216:217], off
	s_add_i32 m0, s12, 0x2000
	s_add_u32 s10, s10, 0x180080
	v_lshl_add_u64 v[216:217], v[220:221], 0, s[2:3]
	s_addc_u32 s11, s11, 0
	s_add_i32 s12, s30, s15
	global_load_lds_dwordx4 v[216:217], off
	v_lshl_add_u64 v[216:217], s[10:11], 0, v[134:135]
	s_mov_b32 m0, s12
	s_nop 0
	global_load_lds_dwordx4 v[216:217], off
	v_lshl_add_u64 v[216:217], s[10:11], 0, v[138:139]
	s_add_i32 m0, s12, 0x2000
	s_nop 0
	global_load_lds_dwordx4 v[216:217], off
	v_lshl_add_u64 v[216:217], v[236:237], 0, s[2:3]
	s_mov_b32 m0, s22
	s_nop 0
	global_load_lds_dwordx4 v[216:217], off
	v_lshl_add_u64 v[216:217], v[238:239], 0, s[2:3]
	s_mov_b32 m0, s23
	s_nop 0
	global_load_lds_dwordx4 v[216:217], off
	s_waitcnt vmcnt(8)
	s_waitcnt lgkmcnt(0)
	s_barrier
	s_setprio 1
	s_waitcnt lgkmcnt(0)
	v_mfma_f32_16x16x32_bf16 v[64:67], v[148:151], v[188:191], v[64:67]
	v_mfma_f32_16x16x32_bf16 v[60:63], v[156:159], v[188:191], v[60:63]
	v_mfma_f32_16x16x32_bf16 v[44:47], v[156:159], v[196:199], v[44:47]
	v_mfma_f32_16x16x32_bf16 v[52:55], v[148:151], v[196:199], v[52:55]
	v_mfma_f32_16x16x32_bf16 v[36:39], v[148:151], v[204:207], v[36:39]
	v_mfma_f32_16x16x32_bf16 v[26:29], v[156:159], v[204:207], v[26:29]
	v_mfma_f32_16x16x32_bf16 v[10:13], v[156:159], v[212:215], v[10:13]
	v_mfma_f32_16x16x32_bf16 v[18:21], v[148:151], v[212:215], v[18:21]
	v_mfma_f32_16x16x32_bf16 v[64:67], v[152:155], v[192:195], v[64:67]
	v_mfma_f32_16x16x32_bf16 v[60:63], v[160:163], v[192:195], v[60:63]
	v_mfma_f32_16x16x32_bf16 v[44:47], v[160:163], v[200:203], v[44:47]
	v_mfma_f32_16x16x32_bf16 v[52:55], v[152:155], v[200:203], v[52:55]
	v_mfma_f32_16x16x32_bf16 v[36:39], v[152:155], v[208:211], v[36:39]
	v_mfma_f32_16x16x32_bf16 v[26:29], v[160:163], v[208:211], v[26:29]
	v_mfma_f32_16x16x32_bf16 v[10:13], v[160:163], v[232:235], v[10:13]
	v_mfma_f32_16x16x32_bf16 v[18:21], v[152:155], v[232:235], v[18:21]
	s_setprio 0
	s_setprio 1
	v_mfma_f32_16x16x32_bf16 v[56:59], v[172:175], v[188:191], v[56:59]
	v_mfma_f32_16x16x32_bf16 v[48:51], v[180:183], v[188:191], v[48:51]
	v_mfma_f32_16x16x32_bf16 v[30:33], v[180:183], v[196:199], v[30:33]
	v_mfma_f32_16x16x32_bf16 v[40:43], v[172:175], v[196:199], v[40:43]
	v_mfma_f32_16x16x32_bf16 v[22:25], v[172:175], v[204:207], v[22:25]
	v_mfma_f32_16x16x32_bf16 v[14:17], v[180:183], v[204:207], v[14:17]
	v_mfma_f32_16x16x32_bf16 v[2:5], v[180:183], v[212:215], v[2:5]
	v_mfma_f32_16x16x32_bf16 v[6:9], v[172:175], v[212:215], v[6:9]
	v_mfma_f32_16x16x32_bf16 v[56:59], v[176:179], v[192:195], v[56:59]
	v_mfma_f32_16x16x32_bf16 v[48:51], v[184:187], v[192:195], v[48:51]
	v_mfma_f32_16x16x32_bf16 v[30:33], v[184:187], v[200:203], v[30:33]
	v_mfma_f32_16x16x32_bf16 v[40:43], v[176:179], v[200:203], v[40:43]
	v_mfma_f32_16x16x32_bf16 v[22:25], v[176:179], v[208:211], v[22:25]
	v_mfma_f32_16x16x32_bf16 v[14:17], v[184:187], v[208:211], v[14:17]
	v_mfma_f32_16x16x32_bf16 v[2:5], v[184:187], v[232:235], v[2:5]
	v_mfma_f32_16x16x32_bf16 v[6:9], v[176:179], v[232:235], v[6:9]
	s_setprio 0
	s_barrier
	s_add_i32 s28, s28, 2
	s_add_u32 s8, s8, 0x100
	s_addc_u32 s9, s9, 0
	s_cmp_gt_u32 s28, 29
	s_cbranch_scc0 .LBB0_1446
	s_waitcnt vmcnt(0)
	s_cmpk_lt_u32 s14, 0x100
	s_cbranch_scc0 .LBB0_1449
	s_barrier

.LBB0_1491:
	s_add_u32 s8, s24, s6
	s_addc_u32 s9, s25, s7
	s_add_u32 s8, s8, 0x6a700100
	s_addc_u32 s9, s9, 0
	s_add_u32 s27, s22, s6
	s_addc_u32 s28, s23, s7
	s_add_i32 s29, 0, 0x10000
	s_cmpk_eq_i32 s6, 0x700
	s_cselect_b32 s11, s5, s9
	s_cselect_b32 s10, s4, s8
	v_add_u32_e32 v1, s29, v145
	s_cselect_b32 s9, s1, s28
	s_cselect_b32 s8, s0, s27
	s_add_i32 s27, 0, 0x14000
	ds_read_b128 v[148:151], v1
	ds_read_b128 v[152:155], v1 offset:1024
	ds_read_b128 v[156:159], v1 offset:2048
	ds_read_b128 v[160:163], v1 offset:3072
	v_add_u32_e32 v1, s27, v145
	ds_read_b128 v[172:175], v1
	ds_read_b128 v[176:179], v1 offset:1024
	ds_read_b128 v[180:183], v1 offset:2048
	ds_read_b128 v[184:187], v1 offset:3072
	v_lshl_add_u64 v[216:217], v[142:143], 0, s[6:7]
	s_add_i32 m0, s14, 0xc000
	ds_read_b128 v[188:191], v146
	ds_read_b128 v[192:195], v146 offset:1024
	ds_read_b128 v[196:199], v146 offset:2048
	ds_read_b128 v[200:203], v146 offset:3072
	ds_read_b128 v[204:207], v146 offset:4096
	ds_read_b128 v[208:211], v146 offset:5120
	ds_read_b128 v[212:215], v146 offset:6144
	ds_read_b128 v[232:235], v146 offset:7168
	global_load_lds_dwordx4 v[216:217], off
	v_lshl_add_u64 v[216:217], v[140:141], 0, s[6:7]
	s_add_i32 m0, s14, 0xe000
	s_nop 0
	global_load_lds_dwordx4 v[216:217], off
	s_waitcnt vmcnt(8)
	s_waitcnt lgkmcnt(0)
	s_barrier
	s_setprio 1
	s_waitcnt lgkmcnt(0)
	v_mfma_f32_16x16x32_bf16 v[128:131], v[148:151], v[188:191], v[128:131]
	v_mfma_f32_16x16x32_bf16 v[124:127], v[156:159], v[188:191], v[124:127]
	v_mfma_f32_16x16x32_bf16 v[116:119], v[156:159], v[196:199], v[116:119]
	v_mfma_f32_16x16x32_bf16 v[120:123], v[148:151], v[196:199], v[120:123]
	v_mfma_f32_16x16x32_bf16 v[108:111], v[148:151], v[204:207], v[108:111]
	v_mfma_f32_16x16x32_bf16 v[100:103], v[156:159], v[204:207], v[100:103]
	v_mfma_f32_16x16x32_bf16 v[84:87], v[156:159], v[212:215], v[84:87]
	v_mfma_f32_16x16x32_bf16 v[92:95], v[148:151], v[212:215], v[92:95]
	v_mfma_f32_16x16x32_bf16 v[128:131], v[152:155], v[192:195], v[128:131]
	v_mfma_f32_16x16x32_bf16 v[124:127], v[160:163], v[192:195], v[124:127]
	v_mfma_f32_16x16x32_bf16 v[116:119], v[160:163], v[200:203], v[116:119]
	v_mfma_f32_16x16x32_bf16 v[120:123], v[152:155], v[200:203], v[120:123]
	v_mfma_f32_16x16x32_bf16 v[108:111], v[152:155], v[208:211], v[108:111]
	v_mfma_f32_16x16x32_bf16 v[100:103], v[160:163], v[208:211], v[100:103]
	v_mfma_f32_16x16x32_bf16 v[84:87], v[160:163], v[232:235], v[84:87]
	v_mfma_f32_16x16x32_bf16 v[92:95], v[152:155], v[232:235], v[92:95]
	s_setprio 0
	s_setprio 1
	v_mfma_f32_16x16x32_bf16 v[112:115], v[172:175], v[188:191], v[112:115]
	v_mfma_f32_16x16x32_bf16 v[104:107], v[180:183], v[188:191], v[104:107]
	v_mfma_f32_16x16x32_bf16 v[88:91], v[180:183], v[196:199], v[88:91]
	v_mfma_f32_16x16x32_bf16 v[96:99], v[172:175], v[196:199], v[96:99]
	v_mfma_f32_16x16x32_bf16 v[80:83], v[172:175], v[204:207], v[80:83]
	v_mfma_f32_16x16x32_bf16 v[76:79], v[180:183], v[204:207], v[76:79]
	v_mfma_f32_16x16x32_bf16 v[68:71], v[180:183], v[212:215], v[68:71]
	v_mfma_f32_16x16x32_bf16 v[72:75], v[172:175], v[212:215], v[72:75]
	v_mfma_f32_16x16x32_bf16 v[112:115], v[176:179], v[192:195], v[112:115]
	v_mfma_f32_16x16x32_bf16 v[104:107], v[184:187], v[192:195], v[104:107]
	v_mfma_f32_16x16x32_bf16 v[88:91], v[184:187], v[200:203], v[88:91]
	v_mfma_f32_16x16x32_bf16 v[96:99], v[176:179], v[200:203], v[96:99]
	v_mfma_f32_16x16x32_bf16 v[80:83], v[176:179], v[208:211], v[80:83]
	v_mfma_f32_16x16x32_bf16 v[76:79], v[184:187], v[208:211], v[76:79]
	v_mfma_f32_16x16x32_bf16 v[68:71], v[184:187], v[232:235], v[68:71]
	v_mfma_f32_16x16x32_bf16 v[72:75], v[176:179], v[232:235], v[72:75]
	s_setprio 0
	s_barrier
	s_add_i32 s28, s29, s13
	v_lshl_add_u64 v[216:217], s[8:9], 0, v[134:135]
	s_mov_b32 m0, s28
	ds_read_b128 v[188:191], v146 offset:16384
	ds_read_b128 v[192:195], v146 offset:17408
	ds_read_b128 v[196:199], v146 offset:18432
	ds_read_b128 v[200:203], v146 offset:19456
	ds_read_b128 v[204:207], v146 offset:20480
	ds_read_b128 v[208:211], v146 offset:21504
	ds_read_b128 v[212:215], v146 offset:22528
	ds_read_b128 v[232:235], v146 offset:23552
	global_load_lds_dwordx4 v[216:217], off
	s_add_i32 m0, s28, 0x2000
	s_add_u32 s28, s8, 0x100000
	v_lshl_add_u64 v[220:221], s[8:9], 0, v[138:139]
	s_addc_u32 s29, s9, 0
	s_add_i32 s27, s27, s13
	global_load_lds_dwordx4 v[220:221], off
	v_lshl_add_u64 v[236:237], s[28:29], 0, v[134:135]
	s_mov_b32 m0, s27
	v_lshl_add_u64 v[238:239], s[10:11], 0, v[136:137]
	global_load_lds_dwordx4 v[236:237], off
	v_lshl_add_u64 v[236:237], s[28:29], 0, v[138:139]
	s_add_i32 m0, s27, 0x2000
	s_nop 0
	global_load_lds_dwordx4 v[236:237], off
	v_lshl_add_u64 v[236:237], s[10:11], 0, v[132:133]
	s_mov_b32 m0, s14
	s_nop 0
	global_load_lds_dwordx4 v[236:237], off
	s_mov_b32 m0, s15
	s_nop 0
	global_load_lds_dwordx4 v[238:239], off
	s_waitcnt vmcnt(8)
	s_waitcnt lgkmcnt(0)
	s_barrier
	s_setprio 1
	s_waitcnt lgkmcnt(0)
	v_mfma_f32_16x16x32_bf16 v[64:67], v[148:151], v[188:191], v[64:67]
	v_mfma_f32_16x16x32_bf16 v[60:63], v[156:159], v[188:191], v[60:63]
	v_mfma_f32_16x16x32_bf16 v[52:55], v[156:159], v[196:199], v[52:55]
	v_mfma_f32_16x16x32_bf16 v[56:59], v[148:151], v[196:199], v[56:59]
	v_mfma_f32_16x16x32_bf16 v[40:43], v[148:151], v[204:207], v[40:43]
	v_mfma_f32_16x16x32_bf16 v[36:39], v[156:159], v[204:207], v[36:39]
	v_mfma_f32_16x16x32_bf16 v[18:21], v[156:159], v[212:215], v[18:21]
	v_mfma_f32_16x16x32_bf16 v[22:25], v[148:151], v[212:215], v[22:25]
	v_mfma_f32_16x16x32_bf16 v[64:67], v[152:155], v[192:195], v[64:67]
	v_mfma_f32_16x16x32_bf16 v[60:63], v[160:163], v[192:195], v[60:63]
	v_mfma_f32_16x16x32_bf16 v[52:55], v[160:163], v[200:203], v[52:55]
	v_mfma_f32_16x16x32_bf16 v[56:59], v[152:155], v[200:203], v[56:59]
	v_mfma_f32_16x16x32_bf16 v[40:43], v[152:155], v[208:211], v[40:43]
	v_mfma_f32_16x16x32_bf16 v[36:39], v[160:163], v[208:211], v[36:39]
	v_mfma_f32_16x16x32_bf16 v[18:21], v[160:163], v[232:235], v[18:21]
	v_mfma_f32_16x16x32_bf16 v[22:25], v[152:155], v[232:235], v[22:25]
	s_setprio 0
	s_setprio 1
	v_mfma_f32_16x16x32_bf16 v[48:51], v[172:175], v[188:191], v[48:51]
	v_mfma_f32_16x16x32_bf16 v[44:47], v[180:183], v[188:191], v[44:47]
	v_mfma_f32_16x16x32_bf16 v[26:29], v[180:183], v[196:199], v[26:29]
	v_mfma_f32_16x16x32_bf16 v[30:33], v[172:175], v[196:199], v[30:33]
	v_mfma_f32_16x16x32_bf16 v[14:17], v[172:175], v[204:207], v[14:17]
	v_mfma_f32_16x16x32_bf16 v[10:13], v[180:183], v[204:207], v[10:13]
	v_mfma_f32_16x16x32_bf16 v[2:5], v[180:183], v[212:215], v[2:5]
	v_mfma_f32_16x16x32_bf16 v[6:9], v[172:175], v[212:215], v[6:9]
	v_mfma_f32_16x16x32_bf16 v[48:51], v[176:179], v[192:195], v[48:51]
	v_mfma_f32_16x16x32_bf16 v[44:47], v[184:187], v[192:195], v[44:47]
	v_mfma_f32_16x16x32_bf16 v[26:29], v[184:187], v[200:203], v[26:29]
	v_mfma_f32_16x16x32_bf16 v[30:33], v[176:179], v[200:203], v[30:33]
	v_mfma_f32_16x16x32_bf16 v[14:17], v[176:179], v[208:211], v[14:17]
	v_mfma_f32_16x16x32_bf16 v[10:13], v[184:187], v[208:211], v[10:13]
	v_mfma_f32_16x16x32_bf16 v[2:5], v[184:187], v[232:235], v[2:5]
	v_mfma_f32_16x16x32_bf16 v[6:9], v[176:179], v[232:235], v[6:9]
	s_setprio 0
	s_barrier
	s_add_i32 s27, 0, 0x18000
	v_add_u32_e32 v1, s27, v145
	s_add_i32 s28, 0, 0x1c000
	ds_read_b128 v[148:151], v1
	ds_read_b128 v[152:155], v1 offset:1024
	ds_read_b128 v[156:159], v1 offset:2048
	ds_read_b128 v[160:163], v1 offset:3072
	v_add_u32_e32 v1, s28, v145
	ds_read_b128 v[172:175], v1
	ds_read_b128 v[176:179], v1 offset:1024
	ds_read_b128 v[180:183], v1 offset:2048
	ds_read_b128 v[184:187], v1 offset:3072
	s_add_u32 s10, s10, 0x100000
	s_addc_u32 s11, s11, 0
	s_mov_b32 m0, s16
	v_lshl_add_u64 v[240:241], s[10:11], 0, v[132:133]
	ds_read_b128 v[188:191], v146 offset:32768
	ds_read_b128 v[192:195], v146 offset:33792
	ds_read_b128 v[196:199], v146 offset:34816
	ds_read_b128 v[200:203], v146 offset:35840
	ds_read_b128 v[204:207], v146 offset:36864
	ds_read_b128 v[208:211], v146 offset:37888
	ds_read_b128 v[212:215], v146 offset:38912
	ds_read_b128 v[232:235], v146 offset:39936
	global_load_lds_dwordx4 v[240:241], off
	v_lshl_add_u64 v[240:241], s[10:11], 0, v[136:137]
	s_mov_b32 m0, s17
	s_nop 0
	global_load_lds_dwordx4 v[240:241], off
	s_waitcnt vmcnt(8)
	s_waitcnt lgkmcnt(0)
	s_barrier
	s_setprio 1
	s_waitcnt lgkmcnt(0)
	v_mfma_f32_16x16x32_bf16 v[128:131], v[148:151], v[188:191], v[128:131]
	v_mfma_f32_16x16x32_bf16 v[124:127], v[156:159], v[188:191], v[124:127]
	v_mfma_f32_16x16x32_bf16 v[116:119], v[156:159], v[196:199], v[116:119]
	v_mfma_f32_16x16x32_bf16 v[120:123], v[148:151], v[196:199], v[120:123]
	v_mfma_f32_16x16x32_bf16 v[108:111], v[148:151], v[204:207], v[108:111]
	v_mfma_f32_16x16x32_bf16 v[100:103], v[156:159], v[204:207], v[100:103]
	v_mfma_f32_16x16x32_bf16 v[84:87], v[156:159], v[212:215], v[84:87]
	v_mfma_f32_16x16x32_bf16 v[92:95], v[148:151], v[212:215], v[92:95]
	v_mfma_f32_16x16x32_bf16 v[128:131], v[152:155], v[192:195], v[128:131]
	v_mfma_f32_16x16x32_bf16 v[124:127], v[160:163], v[192:195], v[124:127]
	v_mfma_f32_16x16x32_bf16 v[116:119], v[160:163], v[200:203], v[116:119]
	v_mfma_f32_16x16x32_bf16 v[120:123], v[152:155], v[200:203], v[120:123]
	v_mfma_f32_16x16x32_bf16 v[108:111], v[152:155], v[208:211], v[108:111]
	v_mfma_f32_16x16x32_bf16 v[100:103], v[160:163], v[208:211], v[100:103]
	v_mfma_f32_16x16x32_bf16 v[84:87], v[160:163], v[232:235], v[84:87]
	v_mfma_f32_16x16x32_bf16 v[92:95], v[152:155], v[232:235], v[92:95]
	s_setprio 0
	s_setprio 1
	v_mfma_f32_16x16x32_bf16 v[112:115], v[172:175], v[188:191], v[112:115]
	v_mfma_f32_16x16x32_bf16 v[104:107], v[180:183], v[188:191], v[104:107]
	v_mfma_f32_16x16x32_bf16 v[88:91], v[180:183], v[196:199], v[88:91]
	v_mfma_f32_16x16x32_bf16 v[96:99], v[172:175], v[196:199], v[96:99]
	v_mfma_f32_16x16x32_bf16 v[80:83], v[172:175], v[204:207], v[80:83]
	v_mfma_f32_16x16x32_bf16 v[76:79], v[180:183], v[204:207], v[76:79]
	v_mfma_f32_16x16x32_bf16 v[68:71], v[180:183], v[212:215], v[68:71]
	v_mfma_f32_16x16x32_bf16 v[72:75], v[172:175], v[212:215], v[72:75]
	v_mfma_f32_16x16x32_bf16 v[112:115], v[176:179], v[192:195], v[112:115]
	v_mfma_f32_16x16x32_bf16 v[104:107], v[184:187], v[192:195], v[104:107]
	v_mfma_f32_16x16x32_bf16 v[88:91], v[184:187], v[200:203], v[88:91]
	v_mfma_f32_16x16x32_bf16 v[96:99], v[176:179], v[200:203], v[96:99]
	v_mfma_f32_16x16x32_bf16 v[80:83], v[176:179], v[208:211], v[80:83]
	v_mfma_f32_16x16x32_bf16 v[76:79], v[184:187], v[208:211], v[76:79]
	v_mfma_f32_16x16x32_bf16 v[68:71], v[184:187], v[232:235], v[68:71]
	v_mfma_f32_16x16x32_bf16 v[72:75], v[176:179], v[232:235], v[72:75]
	s_setprio 0
	s_barrier
	s_add_i32 s10, s27, s13
	v_lshl_add_u64 v[216:217], v[216:217], 0, s[2:3]
	s_mov_b32 m0, s10
	ds_read_b128 v[188:191], v146 offset:49152
	ds_read_b128 v[192:195], v146 offset:50176
	ds_read_b128 v[196:199], v146 offset:51200
	ds_read_b128 v[200:203], v146 offset:52224
	ds_read_b128 v[204:207], v146 offset:53248
	ds_read_b128 v[208:211], v146 offset:54272
	ds_read_b128 v[212:215], v146 offset:55296
	ds_read_b128 v[232:235], v146 offset:56320
	global_load_lds_dwordx4 v[216:217], off
	s_add_i32 m0, s10, 0x2000
	s_add_u32 s8, s8, 0x100080
	v_lshl_add_u64 v[216:217], v[220:221], 0, s[2:3]
	s_addc_u32 s9, s9, 0
	s_add_i32 s10, s28, s13
	global_load_lds_dwordx4 v[216:217], off
	v_lshl_add_u64 v[216:217], s[8:9], 0, v[134:135]
	s_mov_b32 m0, s10
	s_nop 0
	global_load_lds_dwordx4 v[216:217], off
	v_lshl_add_u64 v[216:217], s[8:9], 0, v[138:139]
	s_add_i32 m0, s10, 0x2000
	s_nop 0
	global_load_lds_dwordx4 v[216:217], off
	v_lshl_add_u64 v[216:217], v[236:237], 0, s[2:3]
	s_mov_b32 m0, s20
	s_nop 0
	global_load_lds_dwordx4 v[216:217], off
	v_lshl_add_u64 v[216:217], v[238:239], 0, s[2:3]
	s_mov_b32 m0, s21
	s_nop 0
	global_load_lds_dwordx4 v[216:217], off
	s_waitcnt vmcnt(8)
	s_waitcnt lgkmcnt(0)
	s_barrier
	s_setprio 1
	s_waitcnt lgkmcnt(0)
	v_mfma_f32_16x16x32_bf16 v[64:67], v[148:151], v[188:191], v[64:67]
	v_mfma_f32_16x16x32_bf16 v[60:63], v[156:159], v[188:191], v[60:63]
	v_mfma_f32_16x16x32_bf16 v[52:55], v[156:159], v[196:199], v[52:55]
	v_mfma_f32_16x16x32_bf16 v[56:59], v[148:151], v[196:199], v[56:59]
	v_mfma_f32_16x16x32_bf16 v[40:43], v[148:151], v[204:207], v[40:43]
	v_mfma_f32_16x16x32_bf16 v[36:39], v[156:159], v[204:207], v[36:39]
	v_mfma_f32_16x16x32_bf16 v[18:21], v[156:159], v[212:215], v[18:21]
	v_mfma_f32_16x16x32_bf16 v[22:25], v[148:151], v[212:215], v[22:25]
	v_mfma_f32_16x16x32_bf16 v[64:67], v[152:155], v[192:195], v[64:67]
	v_mfma_f32_16x16x32_bf16 v[60:63], v[160:163], v[192:195], v[60:63]
	v_mfma_f32_16x16x32_bf16 v[52:55], v[160:163], v[200:203], v[52:55]
	v_mfma_f32_16x16x32_bf16 v[56:59], v[152:155], v[200:203], v[56:59]
	v_mfma_f32_16x16x32_bf16 v[40:43], v[152:155], v[208:211], v[40:43]
	v_mfma_f32_16x16x32_bf16 v[36:39], v[160:163], v[208:211], v[36:39]
	v_mfma_f32_16x16x32_bf16 v[18:21], v[160:163], v[232:235], v[18:21]
	v_mfma_f32_16x16x32_bf16 v[22:25], v[152:155], v[232:235], v[22:25]
	s_setprio 0
	s_setprio 1
	v_mfma_f32_16x16x32_bf16 v[48:51], v[172:175], v[188:191], v[48:51]
	v_mfma_f32_16x16x32_bf16 v[44:47], v[180:183], v[188:191], v[44:47]
	v_mfma_f32_16x16x32_bf16 v[26:29], v[180:183], v[196:199], v[26:29]
	v_mfma_f32_16x16x32_bf16 v[30:33], v[172:175], v[196:199], v[30:33]
	v_mfma_f32_16x16x32_bf16 v[14:17], v[172:175], v[204:207], v[14:17]
	v_mfma_f32_16x16x32_bf16 v[10:13], v[180:183], v[204:207], v[10:13]
	v_mfma_f32_16x16x32_bf16 v[2:5], v[180:183], v[212:215], v[2:5]
	v_mfma_f32_16x16x32_bf16 v[6:9], v[172:175], v[212:215], v[6:9]
	v_mfma_f32_16x16x32_bf16 v[48:51], v[176:179], v[192:195], v[48:51]
	v_mfma_f32_16x16x32_bf16 v[44:47], v[184:187], v[192:195], v[44:47]
	v_mfma_f32_16x16x32_bf16 v[26:29], v[184:187], v[200:203], v[26:29]
	v_mfma_f32_16x16x32_bf16 v[30:33], v[176:179], v[200:203], v[30:33]
	v_mfma_f32_16x16x32_bf16 v[14:17], v[176:179], v[208:211], v[14:17]
	v_mfma_f32_16x16x32_bf16 v[10:13], v[184:187], v[208:211], v[10:13]
	v_mfma_f32_16x16x32_bf16 v[2:5], v[184:187], v[232:235], v[2:5]
	v_mfma_f32_16x16x32_bf16 v[6:9], v[176:179], v[232:235], v[6:9]
	s_setprio 0
	s_barrier
	s_add_i32 s26, s26, 2
	s_add_u32 s6, s6, 0x100
	s_addc_u32 s7, s7, 0
	s_cmp_gt_u32 s26, 13
	s_cbranch_scc0 .LBB0_1491
	s_waitcnt vmcnt(0)
	s_cmpk_lt_u32 s12, 0x100
	s_cbranch_scc0 .LBB0_1494
	s_barrier

.LBB0_1624:
	s_add_u32 s20, s18, 0x100
	s_addc_u32 s21, s19, 0
	s_add_i32 s50, 0, 0x10000
	s_cmp_eq_u32 s41, 28
	s_cselect_b32 s25, s15, s21
	s_cselect_b32 s24, s14, s20
	v_add_u32_e32 v1, s50, v184
	s_cselect_b32 s23, s17, s40
	s_cselect_b32 s22, s16, s13
	s_add_i32 s51, 0, 0x14000
	s_waitcnt lgkmcnt(0)
	ds_read_b128 v[134:137], v1
	ds_read_b128 v[138:141], v1 offset:1024
	ds_read_b128 v[142:145], v1 offset:2048
	ds_read_b128 v[146:149], v1 offset:3072
	v_add_u32_e32 v1, s51, v184
	ds_read_b128 v[150:153], v1
	ds_read_b128 v[154:157], v1 offset:1024
	ds_read_b128 v[158:161], v1 offset:2048
	ds_read_b128 v[186:189], v1 offset:3072
	v_lshl_add_u64 v[36:37], s[18:19], 0, v[180:181]
	s_add_i32 m0, s29, 0xc000
	ds_read_b128 v[190:193], v185
	ds_read_b128 v[194:197], v185 offset:1024
	ds_read_b128 v[198:201], v185 offset:2048
	ds_read_b128 v[202:205], v185 offset:3072
	ds_read_b128 v[206:209], v185 offset:4096
	ds_read_b128 v[210:213], v185 offset:5120
	ds_read_b128 v[214:217], v185 offset:6144
	ds_read_b128 v[232:235], v185 offset:7168
	global_load_lds_dwordx4 v[36:37], off
	v_lshl_add_u64 v[36:37], s[18:19], 0, v[178:179]
	s_add_i32 m0, s29, 0xe000
	s_nop 0
	global_load_lds_dwordx4 v[36:37], off
	s_waitcnt vmcnt(8)
	s_waitcnt lgkmcnt(0)
	s_barrier
	s_setprio 1
	s_waitcnt lgkmcnt(0)
	v_mfma_f32_16x16x32_bf16 v[130:133], v[134:137], v[190:193], v[130:133]
	v_mfma_f32_16x16x32_bf16 v[126:129], v[142:145], v[190:193], v[126:129]
	v_mfma_f32_16x16x32_bf16 v[118:121], v[142:145], v[198:201], v[118:121]
	v_mfma_f32_16x16x32_bf16 v[122:125], v[134:137], v[198:201], v[122:125]
	v_mfma_f32_16x16x32_bf16 v[114:117], v[134:137], v[206:209], v[114:117]
	v_mfma_f32_16x16x32_bf16 v[110:113], v[142:145], v[206:209], v[110:113]
	v_mfma_f32_16x16x32_bf16 v[102:105], v[142:145], v[214:217], v[102:105]
	v_mfma_f32_16x16x32_bf16 v[106:109], v[134:137], v[214:217], v[106:109]
	v_mfma_f32_16x16x32_bf16 v[130:133], v[138:141], v[194:197], v[130:133]
	v_mfma_f32_16x16x32_bf16 v[126:129], v[146:149], v[194:197], v[126:129]
	v_mfma_f32_16x16x32_bf16 v[118:121], v[146:149], v[202:205], v[118:121]
	v_mfma_f32_16x16x32_bf16 v[122:125], v[138:141], v[202:205], v[122:125]
	v_mfma_f32_16x16x32_bf16 v[114:117], v[138:141], v[210:213], v[114:117]
	v_mfma_f32_16x16x32_bf16 v[110:113], v[146:149], v[210:213], v[110:113]
	v_mfma_f32_16x16x32_bf16 v[102:105], v[146:149], v[232:235], v[102:105]
	v_mfma_f32_16x16x32_bf16 v[106:109], v[138:141], v[232:235], v[106:109]
	s_setprio 0
	s_setprio 1
	v_mfma_f32_16x16x32_bf16 v[98:101], v[150:153], v[190:193], v[98:101]
	v_mfma_f32_16x16x32_bf16 v[94:97], v[158:161], v[190:193], v[94:97]
	v_mfma_f32_16x16x32_bf16 v[86:89], v[158:161], v[198:201], v[86:89]
	v_mfma_f32_16x16x32_bf16 v[90:93], v[150:153], v[198:201], v[90:93]
	v_mfma_f32_16x16x32_bf16 v[82:85], v[150:153], v[206:209], v[82:85]
	v_mfma_f32_16x16x32_bf16 v[78:81], v[158:161], v[206:209], v[78:81]
	v_mfma_f32_16x16x32_bf16 v[70:73], v[158:161], v[214:217], v[70:73]
	v_mfma_f32_16x16x32_bf16 v[74:77], v[150:153], v[214:217], v[74:77]
	v_mfma_f32_16x16x32_bf16 v[98:101], v[154:157], v[194:197], v[98:101]
	v_mfma_f32_16x16x32_bf16 v[94:97], v[186:189], v[194:197], v[94:97]
	v_mfma_f32_16x16x32_bf16 v[86:89], v[186:189], v[202:205], v[86:89]
	v_mfma_f32_16x16x32_bf16 v[90:93], v[154:157], v[202:205], v[90:93]
	v_mfma_f32_16x16x32_bf16 v[82:85], v[154:157], v[210:213], v[82:85]
	v_mfma_f32_16x16x32_bf16 v[78:81], v[186:189], v[210:213], v[78:81]
	v_mfma_f32_16x16x32_bf16 v[70:73], v[186:189], v[232:235], v[70:73]
	v_mfma_f32_16x16x32_bf16 v[74:77], v[154:157], v[232:235], v[74:77]
	s_setprio 0
	s_barrier
	s_add_i32 s18, s50, s28
	v_lshl_add_u64 v[220:221], s[22:23], 0, v[174:175]
	s_mov_b32 m0, s18
	ds_read_b128 v[190:193], v185 offset:16384
	ds_read_b128 v[194:197], v185 offset:17408
	ds_read_b128 v[198:201], v185 offset:18432
	ds_read_b128 v[202:205], v185 offset:19456
	ds_read_b128 v[206:209], v185 offset:20480
	ds_read_b128 v[210:213], v185 offset:21504
	ds_read_b128 v[214:217], v185 offset:22528
	ds_read_b128 v[232:235], v185 offset:23552
	global_load_lds_dwordx4 v[220:221], off
	s_add_i32 m0, s18, 0x2000
	s_add_u32 s18, s22, 0x180000
	v_lshl_add_u64 v[236:237], s[22:23], 0, v[162:163]
	s_addc_u32 s19, s23, 0
	s_add_i32 s50, s51, s28
	global_load_lds_dwordx4 v[236:237], off
	v_lshl_add_u64 v[36:37], s[18:19], 0, v[174:175]
	s_mov_b32 m0, s50
	v_lshl_add_u64 v[238:239], s[24:25], 0, v[176:177]
	global_load_lds_dwordx4 v[36:37], off
	v_lshl_add_u64 v[36:37], s[18:19], 0, v[162:163]
	s_add_i32 m0, s50, 0x2000
	v_lshl_add_u64 v[240:241], s[24:25], 0, v[172:173]
	global_load_lds_dwordx4 v[36:37], off
	s_mov_b32 m0, s29
	s_nop 0
	global_load_lds_dwordx4 v[238:239], off
	s_mov_b32 m0, s30
	s_nop 0
	global_load_lds_dwordx4 v[240:241], off
	s_waitcnt vmcnt(8)
	s_waitcnt lgkmcnt(0)
	s_barrier
	s_setprio 1
	s_waitcnt lgkmcnt(0)
	v_mfma_f32_16x16x32_bf16 v[66:69], v[134:137], v[190:193], v[66:69]
	v_mfma_f32_16x16x32_bf16 v[62:65], v[142:145], v[190:193], v[62:65]
	v_mfma_f32_16x16x32_bf16 v[58:61], v[134:137], v[198:201], v[58:61]
	v_mfma_f32_16x16x32_bf16 v[54:57], v[142:145], v[198:201], v[54:57]
	v_mfma_f32_16x16x32_bf16 v[50:53], v[134:137], v[206:209], v[50:53]
	v_mfma_f32_16x16x32_bf16 v[46:49], v[142:145], v[206:209], v[46:49]
	v_mfma_f32_16x16x32_bf16 v[42:45], v[134:137], v[214:217], v[42:45]
	v_mfma_f32_16x16x32_bf16 v[36:39], v[142:145], v[214:217], v[38:41]
	v_mfma_f32_16x16x32_bf16 v[66:69], v[138:141], v[194:197], v[66:69]
	v_mfma_f32_16x16x32_bf16 v[62:65], v[146:149], v[194:197], v[62:65]
	v_mfma_f32_16x16x32_bf16 v[54:57], v[146:149], v[202:205], v[54:57]
	v_mfma_f32_16x16x32_bf16 v[58:61], v[138:141], v[202:205], v[58:61]
	v_mfma_f32_16x16x32_bf16 v[50:53], v[138:141], v[210:213], v[50:53]
	v_mfma_f32_16x16x32_bf16 v[46:49], v[146:149], v[210:213], v[46:49]
	v_mfma_f32_16x16x32_bf16 v[36:39], v[146:149], v[232:235], v[36:39]
	v_mfma_f32_16x16x32_bf16 v[42:45], v[138:141], v[232:235], v[42:45]
	s_setprio 0
	s_setprio 1
	v_mfma_f32_16x16x32_bf16 v[30:33], v[150:153], v[190:193], v[30:33]
	v_mfma_f32_16x16x32_bf16 v[26:29], v[158:161], v[190:193], v[26:29]
	v_mfma_f32_16x16x32_bf16 v[18:21], v[158:161], v[198:201], v[18:21]
	v_mfma_f32_16x16x32_bf16 v[22:25], v[150:153], v[198:201], v[22:25]
	v_mfma_f32_16x16x32_bf16 v[14:17], v[150:153], v[206:209], v[14:17]
	v_mfma_f32_16x16x32_bf16 v[10:13], v[158:161], v[206:209], v[10:13]
	v_mfma_f32_16x16x32_bf16 v[2:5], v[158:161], v[214:217], v[2:5]
	v_mfma_f32_16x16x32_bf16 v[6:9], v[150:153], v[214:217], v[6:9]
	v_mfma_f32_16x16x32_bf16 v[30:33], v[154:157], v[194:197], v[30:33]
	v_mfma_f32_16x16x32_bf16 v[26:29], v[186:189], v[194:197], v[26:29]
	v_mfma_f32_16x16x32_bf16 v[18:21], v[186:189], v[202:205], v[18:21]
	v_mfma_f32_16x16x32_bf16 v[22:25], v[154:157], v[202:205], v[22:25]
	v_mfma_f32_16x16x32_bf16 v[14:17], v[154:157], v[210:213], v[14:17]
	v_mfma_f32_16x16x32_bf16 v[10:13], v[186:189], v[210:213], v[10:13]
	v_mfma_f32_16x16x32_bf16 v[2:5], v[186:189], v[232:235], v[2:5]
	v_mfma_f32_16x16x32_bf16 v[6:9], v[154:157], v[232:235], v[6:9]
	s_setprio 0
	s_barrier
	s_add_i32 s50, 0, 0x18000
	v_add_u32_e32 v1, s50, v184
	s_add_i32 s51, 0, 0x1c000
	ds_read_b128 v[134:137], v1
	ds_read_b128 v[138:141], v1 offset:1024
	ds_read_b128 v[142:145], v1 offset:2048
	ds_read_b128 v[146:149], v1 offset:3072
	v_add_u32_e32 v1, s51, v184
	ds_read_b128 v[150:153], v1
	ds_read_b128 v[154:157], v1 offset:1024
	ds_read_b128 v[158:161], v1 offset:2048
	ds_read_b128 v[186:189], v1 offset:3072
	s_add_u32 s18, s24, 0x180000
	s_addc_u32 s19, s25, 0
	s_mov_b32 m0, s31
	v_lshl_add_u64 v[40:41], s[18:19], 0, v[176:177]
	ds_read_b128 v[190:193], v185 offset:32768
	ds_read_b128 v[194:197], v185 offset:33792
	ds_read_b128 v[198:201], v185 offset:34816
	ds_read_b128 v[202:205], v185 offset:35840
	ds_read_b128 v[206:209], v185 offset:36864
	ds_read_b128 v[210:213], v185 offset:37888
	ds_read_b128 v[214:217], v185 offset:38912
	ds_read_b128 v[232:235], v185 offset:39936
	global_load_lds_dwordx4 v[40:41], off
	v_lshl_add_u64 v[40:41], s[18:19], 0, v[172:173]
	s_mov_b32 m0, s34
	s_nop 0
	global_load_lds_dwordx4 v[40:41], off
	s_waitcnt vmcnt(8)
	s_waitcnt lgkmcnt(0)
	s_barrier
	s_setprio 1
	s_waitcnt lgkmcnt(0)
	v_mfma_f32_16x16x32_bf16 v[130:133], v[134:137], v[190:193], v[130:133]
	v_mfma_f32_16x16x32_bf16 v[126:129], v[142:145], v[190:193], v[126:129]
	v_mfma_f32_16x16x32_bf16 v[118:121], v[142:145], v[198:201], v[118:121]
	v_mfma_f32_16x16x32_bf16 v[122:125], v[134:137], v[198:201], v[122:125]
	v_mfma_f32_16x16x32_bf16 v[114:117], v[134:137], v[206:209], v[114:117]
	v_mfma_f32_16x16x32_bf16 v[110:113], v[142:145], v[206:209], v[110:113]
	v_mfma_f32_16x16x32_bf16 v[102:105], v[142:145], v[214:217], v[102:105]
	v_mfma_f32_16x16x32_bf16 v[106:109], v[134:137], v[214:217], v[106:109]
	v_mfma_f32_16x16x32_bf16 v[130:133], v[138:141], v[194:197], v[130:133]
	v_mfma_f32_16x16x32_bf16 v[126:129], v[146:149], v[194:197], v[126:129]
	v_mfma_f32_16x16x32_bf16 v[118:121], v[146:149], v[202:205], v[118:121]
	v_mfma_f32_16x16x32_bf16 v[122:125], v[138:141], v[202:205], v[122:125]
	v_mfma_f32_16x16x32_bf16 v[114:117], v[138:141], v[210:213], v[114:117]
	v_mfma_f32_16x16x32_bf16 v[110:113], v[146:149], v[210:213], v[110:113]
	v_mfma_f32_16x16x32_bf16 v[102:105], v[146:149], v[232:235], v[102:105]
	v_mfma_f32_16x16x32_bf16 v[106:109], v[138:141], v[232:235], v[106:109]
	s_setprio 0
	s_setprio 1
	v_mfma_f32_16x16x32_bf16 v[98:101], v[150:153], v[190:193], v[98:101]
	v_mfma_f32_16x16x32_bf16 v[94:97], v[158:161], v[190:193], v[94:97]
	v_mfma_f32_16x16x32_bf16 v[86:89], v[158:161], v[198:201], v[86:89]
	v_mfma_f32_16x16x32_bf16 v[90:93], v[150:153], v[198:201], v[90:93]
	v_mfma_f32_16x16x32_bf16 v[82:85], v[150:153], v[206:209], v[82:85]
	v_mfma_f32_16x16x32_bf16 v[78:81], v[158:161], v[206:209], v[78:81]
	v_mfma_f32_16x16x32_bf16 v[70:73], v[158:161], v[214:217], v[70:73]
	v_mfma_f32_16x16x32_bf16 v[74:77], v[150:153], v[214:217], v[74:77]
	v_mfma_f32_16x16x32_bf16 v[98:101], v[154:157], v[194:197], v[98:101]
	v_mfma_f32_16x16x32_bf16 v[94:97], v[186:189], v[194:197], v[94:97]
	v_mfma_f32_16x16x32_bf16 v[86:89], v[186:189], v[202:205], v[86:89]
	v_mfma_f32_16x16x32_bf16 v[90:93], v[154:157], v[202:205], v[90:93]
	v_mfma_f32_16x16x32_bf16 v[82:85], v[154:157], v[210:213], v[82:85]
	v_mfma_f32_16x16x32_bf16 v[78:81], v[186:189], v[210:213], v[78:81]
	v_mfma_f32_16x16x32_bf16 v[70:73], v[186:189], v[232:235], v[70:73]
	v_mfma_f32_16x16x32_bf16 v[74:77], v[154:157], v[232:235], v[74:77]
	s_setprio 0
	s_barrier
	s_add_i32 s18, s50, s28
	v_lshl_add_u64 v[40:41], v[220:221], 0, s[2:3]
	s_mov_b32 m0, s18
	ds_read_b128 v[190:193], v185 offset:49152
	ds_read_b128 v[194:197], v185 offset:50176
	ds_read_b128 v[198:201], v185 offset:51200
	ds_read_b128 v[202:205], v185 offset:52224
	ds_read_b128 v[206:209], v185 offset:53248
	ds_read_b128 v[210:213], v185 offset:54272
	ds_read_b128 v[214:217], v185 offset:55296
	ds_read_b128 v[232:235], v185 offset:56320
	global_load_lds_dwordx4 v[40:41], off
	s_add_i32 m0, s18, 0x2000
	s_add_u32 s18, s22, 0x180080
	v_lshl_add_u64 v[40:41], v[236:237], 0, s[2:3]
	s_addc_u32 s19, s23, 0
	s_add_i32 s22, s51, s28
	global_load_lds_dwordx4 v[40:41], off
	v_lshl_add_u64 v[40:41], s[18:19], 0, v[174:175]
	s_mov_b32 m0, s22
	s_nop 0
	global_load_lds_dwordx4 v[40:41], off
	v_lshl_add_u64 v[40:41], s[18:19], 0, v[162:163]
	s_add_i32 m0, s22, 0x2000
	s_nop 0
	global_load_lds_dwordx4 v[40:41], off
	v_lshl_add_u64 v[40:41], v[238:239], 0, s[2:3]
	s_mov_b32 m0, s42
	s_nop 0
	global_load_lds_dwordx4 v[40:41], off
	v_lshl_add_u64 v[40:41], v[240:241], 0, s[2:3]
	s_mov_b32 m0, s43
	s_nop 0
	global_load_lds_dwordx4 v[40:41], off
	s_waitcnt vmcnt(8)
	s_waitcnt lgkmcnt(0)
	s_barrier
	s_setprio 1
	s_waitcnt lgkmcnt(0)
	v_mfma_f32_16x16x32_bf16 v[66:69], v[134:137], v[190:193], v[66:69]
	v_mfma_f32_16x16x32_bf16 v[62:65], v[142:145], v[190:193], v[62:65]
	v_mfma_f32_16x16x32_bf16 v[58:61], v[134:137], v[198:201], v[58:61]
	v_mfma_f32_16x16x32_bf16 v[54:57], v[142:145], v[198:201], v[54:57]
	v_mfma_f32_16x16x32_bf16 v[50:53], v[134:137], v[206:209], v[50:53]
	v_mfma_f32_16x16x32_bf16 v[46:49], v[142:145], v[206:209], v[46:49]
	v_mfma_f32_16x16x32_bf16 v[40:43], v[134:137], v[214:217], v[42:45]
	v_mfma_f32_16x16x32_bf16 v[36:39], v[142:145], v[214:217], v[36:39]
	v_mfma_f32_16x16x32_bf16 v[66:69], v[138:141], v[194:197], v[66:69]
	v_mfma_f32_16x16x32_bf16 v[62:65], v[146:149], v[194:197], v[62:65]
	v_mfma_f32_16x16x32_bf16 v[58:61], v[138:141], v[202:205], v[58:61]
	v_mfma_f32_16x16x32_bf16 v[54:57], v[146:149], v[202:205], v[54:57]
	v_mfma_f32_16x16x32_bf16 v[50:53], v[138:141], v[210:213], v[50:53]
	v_mfma_f32_16x16x32_bf16 v[46:49], v[146:149], v[210:213], v[46:49]
	v_mfma_f32_16x16x32_bf16 v[42:45], v[138:141], v[232:235], v[40:43]
	v_mfma_f32_16x16x32_bf16 v[38:41], v[146:149], v[232:235], v[36:39]
	s_setprio 0
	s_setprio 1
	v_mfma_f32_16x16x32_bf16 v[30:33], v[150:153], v[190:193], v[30:33]
	v_mfma_f32_16x16x32_bf16 v[26:29], v[158:161], v[190:193], v[26:29]
	v_mfma_f32_16x16x32_bf16 v[18:21], v[158:161], v[198:201], v[18:21]
	v_mfma_f32_16x16x32_bf16 v[22:25], v[150:153], v[198:201], v[22:25]
	v_mfma_f32_16x16x32_bf16 v[14:17], v[150:153], v[206:209], v[14:17]
	v_mfma_f32_16x16x32_bf16 v[10:13], v[158:161], v[206:209], v[10:13]
	v_mfma_f32_16x16x32_bf16 v[2:5], v[158:161], v[214:217], v[2:5]
	v_mfma_f32_16x16x32_bf16 v[6:9], v[150:153], v[214:217], v[6:9]
	v_mfma_f32_16x16x32_bf16 v[30:33], v[154:157], v[194:197], v[30:33]
	v_mfma_f32_16x16x32_bf16 v[26:29], v[186:189], v[194:197], v[26:29]
	v_mfma_f32_16x16x32_bf16 v[18:21], v[186:189], v[202:205], v[18:21]
	v_mfma_f32_16x16x32_bf16 v[22:25], v[154:157], v[202:205], v[22:25]
	v_mfma_f32_16x16x32_bf16 v[14:17], v[154:157], v[210:213], v[14:17]
	v_mfma_f32_16x16x32_bf16 v[10:13], v[186:189], v[210:213], v[10:13]
	v_mfma_f32_16x16x32_bf16 v[2:5], v[186:189], v[232:235], v[2:5]
	v_mfma_f32_16x16x32_bf16 v[6:9], v[154:157], v[232:235], v[6:9]
	s_setprio 0
	s_barrier
	s_add_i32 s41, s41, 2
	s_add_u32 s13, s13, 0x100
	s_addc_u32 s40, s40, 0
	s_cmp_gt_u32 s41, 29
	s_mov_b64 s[18:19], s[20:21]
	s_cbranch_scc0 .LBB0_1624
	s_and_b64 vcc, exec, s[10:11]
	s_cbranch_vccz .LBB0_1627
	s_barrier

.LBB0_1732:
	s_add_u32 s20, s18, 0xfff00080
	s_addc_u32 s21, s19, -1
	s_add_i32 s47, 0, 0x10000
	s_cmp_eq_u32 s46, 60
	s_cselect_b32 s23, s13, s21
	s_cselect_b32 s22, s42, s20
	v_add_u32_e32 v1, s47, v144
	s_cselect_b32 s21, s11, s45
	s_cselect_b32 s20, s43, s44
	s_add_i32 s50, 0, 0x14000
	ds_read_b128 v[148:151], v1
	ds_read_b128 v[152:155], v1 offset:1024
	ds_read_b128 v[156:159], v1 offset:2048
	ds_read_b128 v[160:163], v1 offset:3072
	v_add_u32_e32 v1, s50, v144
	ds_read_b128 v[172:175], v1
	ds_read_b128 v[176:179], v1 offset:1024
	ds_read_b128 v[180:183], v1 offset:2048
	ds_read_b128 v[184:187], v1 offset:3072
	v_lshl_add_u64 v[216:217], s[18:19], 0, v[142:143]
	s_add_i32 m0, s29, 0xc000
	ds_read_b128 v[188:191], v146
	ds_read_b128 v[192:195], v146 offset:1024
	ds_read_b128 v[196:199], v146 offset:2048
	ds_read_b128 v[200:203], v146 offset:3072
	ds_read_b128 v[204:207], v146 offset:4096
	ds_read_b128 v[208:211], v146 offset:5120
	ds_read_b128 v[212:215], v146 offset:6144
	ds_read_b128 v[232:235], v146 offset:7168
	global_load_lds_dwordx4 v[216:217], off
	v_lshl_add_u64 v[216:217], s[18:19], 0, v[140:141]
	s_add_i32 m0, s29, 0xe000
	s_nop 0
	global_load_lds_dwordx4 v[216:217], off
	s_waitcnt vmcnt(8)
	s_waitcnt lgkmcnt(0)
	s_barrier
	s_setprio 1
	s_waitcnt lgkmcnt(0)
	v_mfma_f32_16x16x32_bf16 v[128:131], v[148:151], v[188:191], v[128:131]
	v_mfma_f32_16x16x32_bf16 v[124:127], v[156:159], v[188:191], v[124:127]
	v_mfma_f32_16x16x32_bf16 v[116:119], v[156:159], v[196:199], v[116:119]
	v_mfma_f32_16x16x32_bf16 v[120:123], v[148:151], v[196:199], v[120:123]
	v_mfma_f32_16x16x32_bf16 v[104:107], v[148:151], v[204:207], v[104:107]
	v_mfma_f32_16x16x32_bf16 v[100:103], v[156:159], v[204:207], v[100:103]
	v_mfma_f32_16x16x32_bf16 v[84:87], v[156:159], v[212:215], v[84:87]
	v_mfma_f32_16x16x32_bf16 v[88:91], v[148:151], v[212:215], v[88:91]
	v_mfma_f32_16x16x32_bf16 v[128:131], v[152:155], v[192:195], v[128:131]
	v_mfma_f32_16x16x32_bf16 v[124:127], v[160:163], v[192:195], v[124:127]
	v_mfma_f32_16x16x32_bf16 v[116:119], v[160:163], v[200:203], v[116:119]
	v_mfma_f32_16x16x32_bf16 v[120:123], v[152:155], v[200:203], v[120:123]
	v_mfma_f32_16x16x32_bf16 v[104:107], v[152:155], v[208:211], v[104:107]
	v_mfma_f32_16x16x32_bf16 v[100:103], v[160:163], v[208:211], v[100:103]
	v_mfma_f32_16x16x32_bf16 v[84:87], v[160:163], v[232:235], v[84:87]
	v_mfma_f32_16x16x32_bf16 v[88:91], v[152:155], v[232:235], v[88:91]
	s_setprio 0
	s_setprio 1
	v_mfma_f32_16x16x32_bf16 v[112:115], v[172:175], v[188:191], v[112:115]
	v_mfma_f32_16x16x32_bf16 v[108:111], v[180:183], v[188:191], v[108:111]
	v_mfma_f32_16x16x32_bf16 v[92:95], v[180:183], v[196:199], v[92:95]
	v_mfma_f32_16x16x32_bf16 v[96:99], v[172:175], v[196:199], v[96:99]
	v_mfma_f32_16x16x32_bf16 v[80:83], v[172:175], v[204:207], v[80:83]
	v_mfma_f32_16x16x32_bf16 v[76:79], v[180:183], v[204:207], v[76:79]
	v_mfma_f32_16x16x32_bf16 v[68:71], v[180:183], v[212:215], v[68:71]
	v_mfma_f32_16x16x32_bf16 v[72:75], v[172:175], v[212:215], v[72:75]
	v_mfma_f32_16x16x32_bf16 v[112:115], v[176:179], v[192:195], v[112:115]
	v_mfma_f32_16x16x32_bf16 v[108:111], v[184:187], v[192:195], v[108:111]
	v_mfma_f32_16x16x32_bf16 v[92:95], v[184:187], v[200:203], v[92:95]
	v_mfma_f32_16x16x32_bf16 v[96:99], v[176:179], v[200:203], v[96:99]
	v_mfma_f32_16x16x32_bf16 v[80:83], v[176:179], v[208:211], v[80:83]
	v_mfma_f32_16x16x32_bf16 v[76:79], v[184:187], v[208:211], v[76:79]
	v_mfma_f32_16x16x32_bf16 v[68:71], v[184:187], v[232:235], v[68:71]
	v_mfma_f32_16x16x32_bf16 v[72:75], v[176:179], v[232:235], v[72:75]
	s_setprio 0
	s_barrier
	s_add_i32 s47, s47, s26
	v_lshl_add_u64 v[216:217], s[20:21], 0, v[136:137]
	s_mov_b32 m0, s47
	ds_read_b128 v[188:191], v146 offset:16384
	ds_read_b128 v[192:195], v146 offset:17408
	ds_read_b128 v[196:199], v146 offset:18432
	ds_read_b128 v[200:203], v146 offset:19456
	ds_read_b128 v[204:207], v146 offset:20480
	ds_read_b128 v[208:211], v146 offset:21504
	ds_read_b128 v[212:215], v146 offset:22528
	ds_read_b128 v[232:235], v146 offset:23552
	global_load_lds_dwordx4 v[216:217], off
	s_add_i32 m0, s47, 0x2000
	s_add_u32 s48, s20, 0x100000
	v_lshl_add_u64 v[220:221], s[20:21], 0, v[132:133]
	s_addc_u32 s49, s21, 0
	s_add_i32 s47, s50, s26
	global_load_lds_dwordx4 v[220:221], off
	v_lshl_add_u64 v[236:237], s[48:49], 0, v[136:137]
	s_mov_b32 m0, s47
	v_lshl_add_u64 v[238:239], s[22:23], 0, v[134:135]
	global_load_lds_dwordx4 v[236:237], off
	v_lshl_add_u64 v[236:237], s[48:49], 0, v[132:133]
	s_add_i32 m0, s47, 0x2000
	s_nop 0
	global_load_lds_dwordx4 v[236:237], off
	v_lshl_add_u64 v[236:237], s[22:23], 0, v[138:139]
	s_mov_b32 m0, s29
	s_nop 0
	global_load_lds_dwordx4 v[236:237], off
	s_mov_b32 m0, s30
	s_nop 0
	global_load_lds_dwordx4 v[238:239], off
	s_waitcnt vmcnt(8)
	s_waitcnt lgkmcnt(0)
	s_barrier
	s_setprio 1
	s_waitcnt lgkmcnt(0)
	v_mfma_f32_16x16x32_bf16 v[60:63], v[148:151], v[188:191], v[60:63]
	v_mfma_f32_16x16x32_bf16 v[56:59], v[156:159], v[188:191], v[56:59]
	v_mfma_f32_16x16x32_bf16 v[40:43], v[156:159], v[196:199], v[40:43]
	v_mfma_f32_16x16x32_bf16 v[44:47], v[148:151], v[196:199], v[44:47]
	v_mfma_f32_16x16x32_bf16 v[26:29], v[148:151], v[204:207], v[26:29]
	v_mfma_f32_16x16x32_bf16 v[22:25], v[156:159], v[204:207], v[22:25]
	v_mfma_f32_16x16x32_bf16 v[6:9], v[156:159], v[212:215], v[6:9]
	v_mfma_f32_16x16x32_bf16 v[10:13], v[148:151], v[212:215], v[10:13]
	v_mfma_f32_16x16x32_bf16 v[60:63], v[152:155], v[192:195], v[60:63]
	v_mfma_f32_16x16x32_bf16 v[56:59], v[160:163], v[192:195], v[56:59]
	v_mfma_f32_16x16x32_bf16 v[40:43], v[160:163], v[200:203], v[40:43]
	v_mfma_f32_16x16x32_bf16 v[44:47], v[152:155], v[200:203], v[44:47]
	v_mfma_f32_16x16x32_bf16 v[26:29], v[152:155], v[208:211], v[26:29]
	v_mfma_f32_16x16x32_bf16 v[22:25], v[160:163], v[208:211], v[22:25]
	v_mfma_f32_16x16x32_bf16 v[6:9], v[160:163], v[232:235], v[6:9]
	v_mfma_f32_16x16x32_bf16 v[10:13], v[152:155], v[232:235], v[10:13]
	s_setprio 0
	s_setprio 1
	v_mfma_f32_16x16x32_bf16 v[36:39], v[172:175], v[188:191], v[36:39]
	v_mfma_f32_16x16x32_bf16 v[30:33], v[180:183], v[188:191], v[30:33]
	v_mfma_f32_16x16x32_bf16 v[14:17], v[180:183], v[196:199], v[14:17]
	v_mfma_f32_16x16x32_bf16 v[18:21], v[172:175], v[196:199], v[18:21]
	v_mfma_f32_16x16x32_bf16 v[2:5], v[172:175], v[204:207], v[2:5]
	v_mfma_f32_16x16x32_bf16 v[64:67], v[180:183], v[204:207], v[64:67]
	v_mfma_f32_16x16x32_bf16 v[52:55], v[180:183], v[212:215], v[52:55]
	v_mfma_f32_16x16x32_bf16 v[48:51], v[172:175], v[212:215], v[48:51]
	v_mfma_f32_16x16x32_bf16 v[36:39], v[176:179], v[192:195], v[36:39]
	v_mfma_f32_16x16x32_bf16 v[30:33], v[184:187], v[192:195], v[30:33]
	v_mfma_f32_16x16x32_bf16 v[14:17], v[184:187], v[200:203], v[14:17]
	v_mfma_f32_16x16x32_bf16 v[18:21], v[176:179], v[200:203], v[18:21]
	v_mfma_f32_16x16x32_bf16 v[2:5], v[176:179], v[208:211], v[2:5]
	v_mfma_f32_16x16x32_bf16 v[64:67], v[184:187], v[208:211], v[64:67]
	v_mfma_f32_16x16x32_bf16 v[52:55], v[184:187], v[232:235], v[52:55]
	v_mfma_f32_16x16x32_bf16 v[48:51], v[176:179], v[232:235], v[48:51]
	s_setprio 0
	s_barrier
	s_add_i32 s47, 0, 0x18000
	v_add_u32_e32 v1, s47, v144
	s_add_i32 s48, 0, 0x1c000
	ds_read_b128 v[148:151], v1
	ds_read_b128 v[152:155], v1 offset:1024
	ds_read_b128 v[156:159], v1 offset:2048
	ds_read_b128 v[160:163], v1 offset:3072
	v_add_u32_e32 v1, s48, v144
	ds_read_b128 v[172:175], v1
	ds_read_b128 v[176:179], v1 offset:1024
	ds_read_b128 v[180:183], v1 offset:2048
	ds_read_b128 v[184:187], v1 offset:3072
	s_add_u32 s22, s22, 0x100000
	s_addc_u32 s23, s23, 0
	s_mov_b32 m0, s31
	v_lshl_add_u64 v[240:241], s[22:23], 0, v[138:139]
	ds_read_b128 v[188:191], v146 offset:32768
	ds_read_b128 v[192:195], v146 offset:33792
	ds_read_b128 v[196:199], v146 offset:34816
	ds_read_b128 v[200:203], v146 offset:35840
	ds_read_b128 v[204:207], v146 offset:36864
	ds_read_b128 v[208:211], v146 offset:37888
	ds_read_b128 v[212:215], v146 offset:38912
	ds_read_b128 v[232:235], v146 offset:39936
	global_load_lds_dwordx4 v[240:241], off
	v_lshl_add_u64 v[240:241], s[22:23], 0, v[134:135]
	s_mov_b32 m0, s34
	s_nop 0
	global_load_lds_dwordx4 v[240:241], off
	s_waitcnt vmcnt(8)
	s_waitcnt lgkmcnt(0)
	s_barrier
	s_setprio 1
	s_waitcnt lgkmcnt(0)
	v_mfma_f32_16x16x32_bf16 v[128:131], v[148:151], v[188:191], v[128:131]
	v_mfma_f32_16x16x32_bf16 v[124:127], v[156:159], v[188:191], v[124:127]
	v_mfma_f32_16x16x32_bf16 v[116:119], v[156:159], v[196:199], v[116:119]
	v_mfma_f32_16x16x32_bf16 v[120:123], v[148:151], v[196:199], v[120:123]
	v_mfma_f32_16x16x32_bf16 v[104:107], v[148:151], v[204:207], v[104:107]
	v_mfma_f32_16x16x32_bf16 v[100:103], v[156:159], v[204:207], v[100:103]
	v_mfma_f32_16x16x32_bf16 v[84:87], v[156:159], v[212:215], v[84:87]
	v_mfma_f32_16x16x32_bf16 v[88:91], v[148:151], v[212:215], v[88:91]
	v_mfma_f32_16x16x32_bf16 v[128:131], v[152:155], v[192:195], v[128:131]
	v_mfma_f32_16x16x32_bf16 v[124:127], v[160:163], v[192:195], v[124:127]
	v_mfma_f32_16x16x32_bf16 v[116:119], v[160:163], v[200:203], v[116:119]
	v_mfma_f32_16x16x32_bf16 v[120:123], v[152:155], v[200:203], v[120:123]
	v_mfma_f32_16x16x32_bf16 v[104:107], v[152:155], v[208:211], v[104:107]
	v_mfma_f32_16x16x32_bf16 v[100:103], v[160:163], v[208:211], v[100:103]
	v_mfma_f32_16x16x32_bf16 v[84:87], v[160:163], v[232:235], v[84:87]
	v_mfma_f32_16x16x32_bf16 v[88:91], v[152:155], v[232:235], v[88:91]
	s_setprio 0
	s_setprio 1
	v_mfma_f32_16x16x32_bf16 v[112:115], v[172:175], v[188:191], v[112:115]
	v_mfma_f32_16x16x32_bf16 v[108:111], v[180:183], v[188:191], v[108:111]
	v_mfma_f32_16x16x32_bf16 v[92:95], v[180:183], v[196:199], v[92:95]
	v_mfma_f32_16x16x32_bf16 v[96:99], v[172:175], v[196:199], v[96:99]
	v_mfma_f32_16x16x32_bf16 v[80:83], v[172:175], v[204:207], v[80:83]
	v_mfma_f32_16x16x32_bf16 v[76:79], v[180:183], v[204:207], v[76:79]
	v_mfma_f32_16x16x32_bf16 v[68:71], v[180:183], v[212:215], v[68:71]
	v_mfma_f32_16x16x32_bf16 v[72:75], v[172:175], v[212:215], v[72:75]
	v_mfma_f32_16x16x32_bf16 v[112:115], v[176:179], v[192:195], v[112:115]
	v_mfma_f32_16x16x32_bf16 v[108:111], v[184:187], v[192:195], v[108:111]
	v_mfma_f32_16x16x32_bf16 v[92:95], v[184:187], v[200:203], v[92:95]
	v_mfma_f32_16x16x32_bf16 v[96:99], v[176:179], v[200:203], v[96:99]
	v_mfma_f32_16x16x32_bf16 v[80:83], v[176:179], v[208:211], v[80:83]
	v_mfma_f32_16x16x32_bf16 v[76:79], v[184:187], v[208:211], v[76:79]
	v_mfma_f32_16x16x32_bf16 v[68:71], v[184:187], v[232:235], v[68:71]
	v_mfma_f32_16x16x32_bf16 v[72:75], v[176:179], v[232:235], v[72:75]
	s_setprio 0
	s_barrier
	s_add_i32 s22, s47, s26
	v_lshl_add_u64 v[216:217], v[216:217], 0, s[2:3]
	s_mov_b32 m0, s22
	ds_read_b128 v[188:191], v146 offset:49152
	ds_read_b128 v[192:195], v146 offset:50176
	ds_read_b128 v[196:199], v146 offset:51200
	ds_read_b128 v[200:203], v146 offset:52224
	ds_read_b128 v[204:207], v146 offset:53248
	ds_read_b128 v[208:211], v146 offset:54272
	ds_read_b128 v[212:215], v146 offset:55296
	ds_read_b128 v[232:235], v146 offset:56320
	global_load_lds_dwordx4 v[216:217], off
	s_add_i32 m0, s22, 0x2000
	s_add_u32 s20, s20, 0x100080
	v_lshl_add_u64 v[216:217], v[220:221], 0, s[2:3]
	s_addc_u32 s21, s21, 0
	s_add_i32 s22, s48, s26
	global_load_lds_dwordx4 v[216:217], off
	v_lshl_add_u64 v[216:217], s[20:21], 0, v[136:137]
	s_mov_b32 m0, s22
	s_nop 0
	global_load_lds_dwordx4 v[216:217], off
	v_lshl_add_u64 v[216:217], s[20:21], 0, v[132:133]
	s_add_i32 m0, s22, 0x2000
	s_nop 0
	global_load_lds_dwordx4 v[216:217], off
	v_lshl_add_u64 v[216:217], v[236:237], 0, s[2:3]
	s_mov_b32 m0, s35
	s_nop 0
	global_load_lds_dwordx4 v[216:217], off
	v_lshl_add_u64 v[216:217], v[238:239], 0, s[2:3]
	s_mov_b32 m0, s38
	s_nop 0
	global_load_lds_dwordx4 v[216:217], off
	s_waitcnt vmcnt(8)
	s_waitcnt lgkmcnt(0)
	s_barrier
	s_setprio 1
	s_waitcnt lgkmcnt(0)
	v_mfma_f32_16x16x32_bf16 v[60:63], v[148:151], v[188:191], v[60:63]
	v_mfma_f32_16x16x32_bf16 v[56:59], v[156:159], v[188:191], v[56:59]
	v_mfma_f32_16x16x32_bf16 v[40:43], v[156:159], v[196:199], v[40:43]
	v_mfma_f32_16x16x32_bf16 v[44:47], v[148:151], v[196:199], v[44:47]
	v_mfma_f32_16x16x32_bf16 v[26:29], v[148:151], v[204:207], v[26:29]
	v_mfma_f32_16x16x32_bf16 v[22:25], v[156:159], v[204:207], v[22:25]
	v_mfma_f32_16x16x32_bf16 v[6:9], v[156:159], v[212:215], v[6:9]
	v_mfma_f32_16x16x32_bf16 v[10:13], v[148:151], v[212:215], v[10:13]
	v_mfma_f32_16x16x32_bf16 v[60:63], v[152:155], v[192:195], v[60:63]
	v_mfma_f32_16x16x32_bf16 v[56:59], v[160:163], v[192:195], v[56:59]
	v_mfma_f32_16x16x32_bf16 v[40:43], v[160:163], v[200:203], v[40:43]
	v_mfma_f32_16x16x32_bf16 v[44:47], v[152:155], v[200:203], v[44:47]
	v_mfma_f32_16x16x32_bf16 v[26:29], v[152:155], v[208:211], v[26:29]
	v_mfma_f32_16x16x32_bf16 v[22:25], v[160:163], v[208:211], v[22:25]
	v_mfma_f32_16x16x32_bf16 v[6:9], v[160:163], v[232:235], v[6:9]
	v_mfma_f32_16x16x32_bf16 v[10:13], v[152:155], v[232:235], v[10:13]
	s_setprio 0
	s_setprio 1
	v_mfma_f32_16x16x32_bf16 v[36:39], v[172:175], v[188:191], v[36:39]
	v_mfma_f32_16x16x32_bf16 v[30:33], v[180:183], v[188:191], v[30:33]
	v_mfma_f32_16x16x32_bf16 v[14:17], v[180:183], v[196:199], v[14:17]
	v_mfma_f32_16x16x32_bf16 v[18:21], v[172:175], v[196:199], v[18:21]
	v_mfma_f32_16x16x32_bf16 v[2:5], v[172:175], v[204:207], v[2:5]
	v_mfma_f32_16x16x32_bf16 v[64:67], v[180:183], v[204:207], v[64:67]
	v_mfma_f32_16x16x32_bf16 v[52:55], v[180:183], v[212:215], v[52:55]
	v_mfma_f32_16x16x32_bf16 v[48:51], v[172:175], v[212:215], v[48:51]
	v_mfma_f32_16x16x32_bf16 v[36:39], v[176:179], v[192:195], v[36:39]
	v_mfma_f32_16x16x32_bf16 v[30:33], v[184:187], v[192:195], v[30:33]
	v_mfma_f32_16x16x32_bf16 v[14:17], v[184:187], v[200:203], v[14:17]
	v_mfma_f32_16x16x32_bf16 v[18:21], v[176:179], v[200:203], v[18:21]
	v_mfma_f32_16x16x32_bf16 v[2:5], v[176:179], v[208:211], v[2:5]
	v_mfma_f32_16x16x32_bf16 v[64:67], v[184:187], v[208:211], v[64:67]
	v_mfma_f32_16x16x32_bf16 v[52:55], v[184:187], v[232:235], v[52:55]
	v_mfma_f32_16x16x32_bf16 v[48:51], v[176:179], v[232:235], v[48:51]
	s_setprio 0
	s_barrier
	s_add_i32 s46, s46, 2
	s_add_u32 s44, s44, 0x100
	s_addc_u32 s45, s45, 0
	s_add_u32 s18, s18, 0x100
	s_addc_u32 s19, s19, 0
	s_cmp_gt_u32 s46, 61
	s_cbranch_scc0 .LBB0_1732
	s_and_b64 vcc, exec, s[8:9]
	s_cbranch_vccz .LBB0_1735
	s_barrier
